# removed all s_setprio from the 8 GEMM K-loops (on top of MFMA pair-snake order)
# speedup vs baseline: 1.0019x; 1.0019x over previous
; #define PG8_LAS __attribute__((address_space(3)))
; #define PG8_STAGE(bufoff, gbase, voff) do { _Pragma("unroll") for (int _i = 0; _i < 2; ++_i) \
;         __builtin_amdgcn_global_load_lds((const unsigned*)((const char*)(gbase) + (voff)[_i]), (PG8_LAS unsigned*)(lds + (bufoff) + ldsw + _i * 8192), 16, 0, 0); } while (0)
; #define PG8_LDA(dst, b, h) do { _Pragma("unroll") for (int m = 0; m < 4; ++m) _Pragma("unroll") for (int k = 0; k < 2; ++k) dst[m][k] = *(const PG8_LAS bf16x8*)(lds + PG8_SA(b, h) + aoff + m * 2048 + k * 1024); } while (0)
; #define PG8_LDB(dst, b, h) do { _Pragma("unroll") for (int n = 0; n < 2; ++n) _Pragma("unroll") for (int k = 0; k < 2; ++k) dst[n][k] = *(const PG8_LAS bf16x8*)(lds + PG8_SB(b, h) + boff + n * 2048 + k * 1024); } while (0)
; #define PG8_WAIT_V(n) asm volatile("s_waitcnt vmcnt(" #n ")" ::: "memory")
; #define PG8_WAIT_L(n) asm volatile("s_waitcnt lgkmcnt(" #n ")" ::: "memory")
; #define PG8_BAR __builtin_amdgcn_s_barrier()
; #define PG8_SCHED __builtin_amdgcn_sched_barrier(0)
; template <class Epi, class Sched, bool ALIGN_EPI = false, bool SP2 = false>
; __device__ __forceinline__ void gemm_phase(PG8_LAS unsigned char* lds, const Gemm g, const Sched& S, const Epi& E, int wave_s) {
;     ...
;         for (int t = 0; t < nt; t += 2) {
;             const bool last = (t == nt - 2);
;             if constexpr (Epi::NEED_RS) { if (t == 0 && wid < 4) __builtin_amdgcn_global_load_lds((const unsigned*)(E.rstd + cur.pm * BM + wid * 64 + lane), (PG8_LAS unsigned*)(rsl + wid * 64), 4, 0, 0); }
;             const char* a1 = cA + (size_t)(t + 1) * kstep;
;             const char* a2 = last ? nA : cA + (size_t)(t + 2) * kstep; const char* b2 = last ? nB : cB + (size_t)(t + 2) * kstep;
;             const char* a3 = a2 + kstep; const char* b3 = b2 + kstep;
;             if (last && has_next) S.a_ready(nxt);
;             if constexpr (SP2) {
;             PG8_LDB(B0, 0, 0); PG8_LDB(B1, 0, 1); PG8_SCHED; PG8_LDA(At, 0, 0); PG8_STAGE(PG8_SA(1, 1), a1 + hstep, voffA);
;             PG8_WAIT_V(8); PG8_WAIT_L(0); PG8_BAR; PG8_MMA(0, 0, At, B0); PG8_MMA(0, 1, At, B1); PG8_BAR; PG8_SCHED;
;             PG8_LDA(At, 0, 1); PG8_STAGE(PG8_SB(0, 0), b2, voffB); PG8_STAGE(PG8_SB(0, 1), b2 + hstep, voffB); PG8_STAGE(PG8_SA(0, 0), a2, voffA);
.LBB0_41:
	ds_read_b128 v[144:147], v158 offset:3072
	ds_read_b128 v[148:151], v158 offset:2048
	ds_read_b128 v[152:155], v158 offset:1024
	ds_read_b128 v[160:163], v158
	ds_read_b128 v[164:167], v157 offset:3072
	ds_read_b128 v[168:171], v157 offset:2048
	ds_read_b128 v[172:175], v157 offset:1024
	ds_read_b128 v[176:179], v157
	s_add_u32 s48, s46, 0xfff00080
	s_addc_u32 s49, s47, -1
	s_cmp_eq_u32 s86, 60
	s_cselect_b32 s51, s31, s49
	s_cselect_b32 s50, s72, s48
	s_cselect_b32 s49, s35, s85
	s_cselect_b32 s48, s73, s84
	s_mov_b32 m0, s74
	v_lshl_add_u64 v[212:213], s[46:47], 0, v[138:139]
	ds_read_b128 v[180:183], v159
	ds_read_b128 v[184:187], v159 offset:1024
	ds_read_b128 v[188:191], v159 offset:2048
	ds_read_b128 v[192:195], v159 offset:3072
	ds_read_b128 v[196:199], v159 offset:4096
	ds_read_b128 v[200:203], v159 offset:5120
	ds_read_b128 v[204:207], v159 offset:6144
	ds_read_b128 v[208:211], v159 offset:7168
	global_load_lds_dwordx4 v[212:213], off
	v_lshl_add_u64 v[212:213], s[46:47], 0, v[140:141]
	s_mov_b32 m0, s75
	s_nop 0
	global_load_lds_dwordx4 v[212:213], off
	s_waitcnt vmcnt(8)
	s_waitcnt lgkmcnt(0)
	s_barrier
	v_mfma_f32_16x16x32_bf16 v[124:127], v[176:179], v[180:183], v[124:127]
	v_mfma_f32_16x16x32_bf16 v[124:127], v[172:175], v[184:187], v[124:127]
	v_mfma_f32_16x16x32_bf16 v[120:123], v[164:167], v[184:187], v[120:123]
	v_mfma_f32_16x16x32_bf16 v[120:123], v[168:171], v[180:183], v[120:123]
	v_mfma_f32_16x16x32_bf16 v[104:107], v[168:171], v[188:191], v[104:107]
	v_mfma_f32_16x16x32_bf16 v[104:107], v[164:167], v[192:195], v[104:107]
	v_mfma_f32_16x16x32_bf16 v[108:111], v[172:175], v[192:195], v[108:111]
	v_mfma_f32_16x16x32_bf16 v[108:111], v[176:179], v[188:191], v[108:111]
	v_mfma_f32_16x16x32_bf16 v[92:95], v[176:179], v[196:199], v[92:95]
	v_mfma_f32_16x16x32_bf16 v[92:95], v[172:175], v[200:203], v[92:95]
	v_mfma_f32_16x16x32_bf16 v[88:91], v[164:167], v[200:203], v[88:91]
	v_mfma_f32_16x16x32_bf16 v[88:91], v[168:171], v[196:199], v[88:91]
	v_mfma_f32_16x16x32_bf16 v[56:59], v[168:171], v[204:207], v[56:59]
	v_mfma_f32_16x16x32_bf16 v[56:59], v[164:167], v[208:211], v[56:59]
	v_mfma_f32_16x16x32_bf16 v[64:67], v[172:175], v[208:211], v[64:67]
	v_mfma_f32_16x16x32_bf16 v[64:67], v[176:179], v[204:207], v[64:67]
	v_mfma_f32_16x16x32_bf16 v[116:119], v[160:163], v[180:183], v[116:119]
	v_mfma_f32_16x16x32_bf16 v[116:119], v[152:155], v[184:187], v[116:119]
	v_mfma_f32_16x16x32_bf16 v[112:115], v[144:147], v[184:187], v[112:115]
	v_mfma_f32_16x16x32_bf16 v[112:115], v[148:151], v[180:183], v[112:115]
	v_mfma_f32_16x16x32_bf16 v[96:99], v[148:151], v[188:191], v[96:99]
	v_mfma_f32_16x16x32_bf16 v[96:99], v[144:147], v[192:195], v[96:99]
	v_mfma_f32_16x16x32_bf16 v[100:103], v[152:155], v[192:195], v[100:103]
	v_mfma_f32_16x16x32_bf16 v[100:103], v[160:163], v[188:191], v[100:103]
	v_mfma_f32_16x16x32_bf16 v[84:87], v[160:163], v[196:199], v[84:87]
	v_mfma_f32_16x16x32_bf16 v[84:87], v[152:155], v[200:203], v[84:87]
	v_mfma_f32_16x16x32_bf16 v[80:83], v[144:147], v[200:203], v[80:83]
	v_mfma_f32_16x16x32_bf16 v[80:83], v[148:151], v[196:199], v[80:83]
	v_mfma_f32_16x16x32_bf16 v[48:51], v[148:151], v[204:207], v[48:51]
	v_mfma_f32_16x16x32_bf16 v[48:51], v[144:147], v[208:211], v[48:51]
	v_mfma_f32_16x16x32_bf16 v[52:55], v[152:155], v[208:211], v[52:55]
	v_mfma_f32_16x16x32_bf16 v[52:55], v[160:163], v[204:207], v[52:55]
	s_barrier
	s_mov_b32 m0, s76
	v_lshl_add_u64 v[212:213], s[48:49], 0, v[132:133]
	s_add_u32 s88, s48, 0x100000
	ds_read_b128 v[180:183], v159 offset:16384
	ds_read_b128 v[184:187], v159 offset:17408
	ds_read_b128 v[188:191], v159 offset:18432
	ds_read_b128 v[192:195], v159 offset:19456
	ds_read_b128 v[196:199], v159 offset:20480
	ds_read_b128 v[200:203], v159 offset:21504
	ds_read_b128 v[204:207], v159 offset:22528
	ds_read_b128 v[208:211], v159 offset:23552
	global_load_lds_dwordx4 v[212:213], off
	v_lshl_add_u64 v[214:215], s[48:49], 0, v[128:129]
	s_mov_b32 m0, s77
	s_addc_u32 s89, s49, 0
	global_load_lds_dwordx4 v[214:215], off
	v_lshl_add_u64 v[216:217], s[88:89], 0, v[132:133]
	s_mov_b32 m0, s78
	v_lshl_add_u64 v[218:219], s[50:51], 0, v[130:131]
	global_load_lds_dwordx4 v[216:217], off
	v_lshl_add_u64 v[216:217], s[88:89], 0, v[128:129]
	s_mov_b32 m0, s79
	s_nop 0
	global_load_lds_dwordx4 v[216:217], off
	v_lshl_add_u64 v[216:217], s[50:51], 0, v[134:135]
	s_mov_b32 m0, s43
	s_nop 0
	global_load_lds_dwordx4 v[216:217], off
	s_mov_b32 m0, s57
	s_nop 0
	global_load_lds_dwordx4 v[218:219], off
	s_waitcnt vmcnt(8)
	s_waitcnt lgkmcnt(0)
	s_barrier
; #define PG8_STAGE(bufoff, gbase, voff) do { _Pragma("unroll") for (int _i = 0; _i < 2; ++_i) \
;         __builtin_amdgcn_global_load_lds((const unsigned*)((const char*)(gbase) + (voff)[_i]), (PG8_LAS unsigned*)(lds + (bufoff) + ldsw + _i * 8192), 16, 0, 0); } while (0)
; #define PG8_LDA(dst, b, h) do { _Pragma("unroll") for (int m = 0; m < 4; ++m) _Pragma("unroll") for (int k = 0; k < 2; ++k) dst[m][k] = *(const PG8_LAS bf16x8*)(lds + PG8_SA(b, h) + aoff + m * 2048 + k * 1024); } while (0)
; #define PG8_LDB(dst, b, h) do { _Pragma("unroll") for (int n = 0; n < 2; ++n) _Pragma("unroll") for (int k = 0; k < 2; ++k) dst[n][k] = *(const PG8_LAS bf16x8*)(lds + PG8_SB(b, h) + boff + n * 2048 + k * 1024); } while (0)
; #define PG8_MMA(ai, bj, At, Bt) do { __builtin_amdgcn_s_setprio(1); _Pragma("unroll") for (int m = 0; m < 4; ++m) _Pragma("unroll") for (int n = 0; n < 2; ++n) _Pragma("unroll") for (int k = 0; k < 2; ++k) \
;         acc[ai][bj][m][n] = __builtin_amdgcn_mfma_f32_16x16x32_bf16(Bt[n][k], At[m][k], acc[ai][bj][m][n], 0, 0, 0); __builtin_amdgcn_s_setprio(0); } while (0)
; #define PG8_WAIT_V(n) asm volatile("s_waitcnt vmcnt(" #n ")" ::: "memory")
; #define PG8_WAIT_L(n) asm volatile("s_waitcnt lgkmcnt(" #n ")" ::: "memory")
; #define PG8_BAR __builtin_amdgcn_s_barrier()
; #define PG8_SCHED __builtin_amdgcn_sched_barrier(0)
; template <class Epi, class Sched, bool ALIGN_EPI = false, bool SP2 = false>
; __device__ __forceinline__ void gemm_phase(PG8_LAS unsigned char* lds, const Gemm g, const Sched& S, const Epi& E, int wave_s) {
;     ...
;             PG8_WAIT_V(8); PG8_WAIT_L(0); PG8_BAR; PG8_MMA(1, 0, At, B0); PG8_MMA(1, 1, At, B1); PG8_BAR; PG8_SCHED;
;             PG8_LDB(B0, 1, 0); PG8_LDB(B1, 1, 1); PG8_SCHED; PG8_LDA(At, 1, 0); PG8_STAGE(PG8_SA(0, 1), a2 + hstep, voffA);
;             PG8_WAIT_V(8); PG8_WAIT_L(0); PG8_BAR; PG8_MMA(0, 0, At, B0); PG8_MMA(0, 1, At, B1); PG8_BAR; PG8_SCHED;
	v_mfma_f32_16x16x32_bf16 v[76:79], v[176:179], v[180:183], v[76:79]
	v_mfma_f32_16x16x32_bf16 v[76:79], v[172:175], v[184:187], v[76:79]
	v_mfma_f32_16x16x32_bf16 v[72:75], v[164:167], v[184:187], v[72:75]
	v_mfma_f32_16x16x32_bf16 v[72:75], v[168:171], v[180:183], v[72:75]
	v_mfma_f32_16x16x32_bf16 v[40:43], v[168:171], v[188:191], v[40:43]
	v_mfma_f32_16x16x32_bf16 v[40:43], v[164:167], v[192:195], v[40:43]
	v_mfma_f32_16x16x32_bf16 v[44:47], v[172:175], v[192:195], v[44:47]
	v_mfma_f32_16x16x32_bf16 v[44:47], v[176:179], v[188:191], v[44:47]
	v_mfma_f32_16x16x32_bf16 v[28:31], v[176:179], v[196:199], v[28:31]
	v_mfma_f32_16x16x32_bf16 v[28:31], v[172:175], v[200:203], v[28:31]
	v_mfma_f32_16x16x32_bf16 v[24:27], v[164:167], v[200:203], v[24:27]
	v_mfma_f32_16x16x32_bf16 v[24:27], v[168:171], v[196:199], v[24:27]
	v_mfma_f32_16x16x32_bf16 v[8:11], v[168:171], v[204:207], v[8:11]
	v_mfma_f32_16x16x32_bf16 v[8:11], v[164:167], v[208:211], v[8:11]
	v_mfma_f32_16x16x32_bf16 v[12:15], v[172:175], v[208:211], v[12:15]
	v_mfma_f32_16x16x32_bf16 v[12:15], v[176:179], v[204:207], v[12:15]
	v_mfma_f32_16x16x32_bf16 v[68:71], v[160:163], v[180:183], v[68:71]
	v_mfma_f32_16x16x32_bf16 v[68:71], v[152:155], v[184:187], v[68:71]
	v_mfma_f32_16x16x32_bf16 v[60:63], v[144:147], v[184:187], v[60:63]
	v_mfma_f32_16x16x32_bf16 v[60:63], v[148:151], v[180:183], v[60:63]
	v_mfma_f32_16x16x32_bf16 v[32:35], v[148:151], v[188:191], v[32:35]
	v_mfma_f32_16x16x32_bf16 v[32:35], v[144:147], v[192:195], v[32:35]
	v_mfma_f32_16x16x32_bf16 v[36:39], v[152:155], v[192:195], v[36:39]
	v_mfma_f32_16x16x32_bf16 v[36:39], v[160:163], v[188:191], v[36:39]
	v_mfma_f32_16x16x32_bf16 v[20:23], v[160:163], v[196:199], v[20:23]
	v_mfma_f32_16x16x32_bf16 v[20:23], v[152:155], v[200:203], v[20:23]
	v_mfma_f32_16x16x32_bf16 v[16:19], v[144:147], v[200:203], v[16:19]
	v_mfma_f32_16x16x32_bf16 v[16:19], v[148:151], v[196:199], v[16:19]
	v_mfma_f32_16x16x32_bf16 v[0:3], v[148:151], v[204:207], v[0:3]
	v_mfma_f32_16x16x32_bf16 v[0:3], v[144:147], v[208:211], v[0:3]
	v_mfma_f32_16x16x32_bf16 v[4:7], v[152:155], v[208:211], v[4:7]
	v_mfma_f32_16x16x32_bf16 v[4:7], v[160:163], v[204:207], v[4:7]
	s_barrier
	ds_read_b128 v[144:147], v142
	ds_read_b128 v[148:151], v142 offset:1024
	ds_read_b128 v[152:155], v142 offset:2048
	ds_read_b128 v[160:163], v142 offset:3072
	ds_read_b128 v[164:167], v143
	ds_read_b128 v[168:171], v143 offset:1024
	ds_read_b128 v[172:175], v143 offset:2048
	ds_read_b128 v[176:179], v143 offset:3072
	s_add_u32 s50, s50, 0x100000
	s_addc_u32 s51, s51, 0
	s_mov_b32 m0, s58
	v_lshl_add_u64 v[220:221], s[50:51], 0, v[134:135]
	ds_read_b128 v[180:183], v159 offset:32768
	ds_read_b128 v[184:187], v159 offset:33792
	ds_read_b128 v[188:191], v159 offset:34816
	ds_read_b128 v[192:195], v159 offset:35840
	ds_read_b128 v[196:199], v159 offset:36864
	ds_read_b128 v[200:203], v159 offset:37888
	ds_read_b128 v[204:207], v159 offset:38912
	ds_read_b128 v[208:211], v159 offset:39936
	global_load_lds_dwordx4 v[220:221], off
	v_lshl_add_u64 v[220:221], s[50:51], 0, v[130:131]
	s_mov_b32 m0, s59
	s_nop 0
	global_load_lds_dwordx4 v[220:221], off
	s_waitcnt vmcnt(8)
	s_waitcnt lgkmcnt(0)
	s_barrier
	v_mfma_f32_16x16x32_bf16 v[124:127], v[144:147], v[180:183], v[124:127]
	v_mfma_f32_16x16x32_bf16 v[124:127], v[148:151], v[184:187], v[124:127]
	v_mfma_f32_16x16x32_bf16 v[120:123], v[160:163], v[184:187], v[120:123]
	v_mfma_f32_16x16x32_bf16 v[120:123], v[152:155], v[180:183], v[120:123]
	v_mfma_f32_16x16x32_bf16 v[104:107], v[152:155], v[188:191], v[104:107]
	v_mfma_f32_16x16x32_bf16 v[104:107], v[160:163], v[192:195], v[104:107]
	v_mfma_f32_16x16x32_bf16 v[108:111], v[148:151], v[192:195], v[108:111]
	v_mfma_f32_16x16x32_bf16 v[108:111], v[144:147], v[188:191], v[108:111]
	v_mfma_f32_16x16x32_bf16 v[92:95], v[144:147], v[196:199], v[92:95]
	v_mfma_f32_16x16x32_bf16 v[92:95], v[148:151], v[200:203], v[92:95]
	v_mfma_f32_16x16x32_bf16 v[88:91], v[160:163], v[200:203], v[88:91]
	v_mfma_f32_16x16x32_bf16 v[88:91], v[152:155], v[196:199], v[88:91]
	v_mfma_f32_16x16x32_bf16 v[56:59], v[152:155], v[204:207], v[56:59]
	v_mfma_f32_16x16x32_bf16 v[56:59], v[160:163], v[208:211], v[56:59]
	v_mfma_f32_16x16x32_bf16 v[64:67], v[148:151], v[208:211], v[64:67]
	v_mfma_f32_16x16x32_bf16 v[64:67], v[144:147], v[204:207], v[64:67]
	v_mfma_f32_16x16x32_bf16 v[116:119], v[164:167], v[180:183], v[116:119]
	v_mfma_f32_16x16x32_bf16 v[116:119], v[168:171], v[184:187], v[116:119]
	v_mfma_f32_16x16x32_bf16 v[112:115], v[176:179], v[184:187], v[112:115]
	v_mfma_f32_16x16x32_bf16 v[112:115], v[172:175], v[180:183], v[112:115]
	v_mfma_f32_16x16x32_bf16 v[96:99], v[172:175], v[188:191], v[96:99]
	v_mfma_f32_16x16x32_bf16 v[96:99], v[176:179], v[192:195], v[96:99]
	v_mfma_f32_16x16x32_bf16 v[100:103], v[168:171], v[192:195], v[100:103]
	v_mfma_f32_16x16x32_bf16 v[100:103], v[164:167], v[188:191], v[100:103]
	v_mfma_f32_16x16x32_bf16 v[84:87], v[164:167], v[196:199], v[84:87]
	v_mfma_f32_16x16x32_bf16 v[84:87], v[168:171], v[200:203], v[84:87]
	v_mfma_f32_16x16x32_bf16 v[80:83], v[176:179], v[200:203], v[80:83]
	v_mfma_f32_16x16x32_bf16 v[80:83], v[172:175], v[196:199], v[80:83]
	v_mfma_f32_16x16x32_bf16 v[48:51], v[172:175], v[204:207], v[48:51]
	v_mfma_f32_16x16x32_bf16 v[48:51], v[176:179], v[208:211], v[48:51]
	v_mfma_f32_16x16x32_bf16 v[52:55], v[168:171], v[208:211], v[52:55]
	v_mfma_f32_16x16x32_bf16 v[52:55], v[164:167], v[204:207], v[52:55]
	s_barrier
; #define PG8_STAGE(bufoff, gbase, voff) do { _Pragma("unroll") for (int _i = 0; _i < 2; ++_i) \
;         __builtin_amdgcn_global_load_lds((const unsigned*)((const char*)(gbase) + (voff)[_i]), (PG8_LAS unsigned*)(lds + (bufoff) + ldsw + _i * 8192), 16, 0, 0); } while (0)
; #define PG8_LDA(dst, b, h) do { _Pragma("unroll") for (int m = 0; m < 4; ++m) _Pragma("unroll") for (int k = 0; k < 2; ++k) dst[m][k] = *(const PG8_LAS bf16x8*)(lds + PG8_SA(b, h) + aoff + m * 2048 + k * 1024); } while (0)
; #define PG8_MMA(ai, bj, At, Bt) do { __builtin_amdgcn_s_setprio(1); _Pragma("unroll") for (int m = 0; m < 4; ++m) _Pragma("unroll") for (int n = 0; n < 2; ++n) _Pragma("unroll") for (int k = 0; k < 2; ++k) \
;         acc[ai][bj][m][n] = __builtin_amdgcn_mfma_f32_16x16x32_bf16(Bt[n][k], At[m][k], acc[ai][bj][m][n], 0, 0, 0); __builtin_amdgcn_s_setprio(0); } while (0)
; #define PG8_WAIT_V(n) asm volatile("s_waitcnt vmcnt(" #n ")" ::: "memory")
; #define PG8_WAIT_L(n) asm volatile("s_waitcnt lgkmcnt(" #n ")" ::: "memory")
; #define PG8_BAR __builtin_amdgcn_s_barrier()
; #define PG8_SCHED __builtin_amdgcn_sched_barrier(0)
; template <class Epi, class Sched, bool ALIGN_EPI = false, bool SP2 = false>
; __device__ __forceinline__ void gemm_phase(PG8_LAS unsigned char* lds, const Gemm g, const Sched& S, const Epi& E, int wave_s) {
;     ...
;             PG8_LDA(At, 1, 1); PG8_STAGE(PG8_SB(1, 0), b3, voffB); PG8_STAGE(PG8_SB(1, 1), b3 + hstep, voffB); PG8_STAGE(PG8_SA(1, 0), a3, voffA);
;             PG8_WAIT_V(8); PG8_WAIT_L(0); PG8_BAR; PG8_MMA(1, 0, At, B0); PG8_MMA(1, 1, At, B1); PG8_BAR; PG8_SCHED;
;     ...
;         if constexpr (ALIGN_EPI) { if (wr == 0) PG8_BAR; }
	s_mov_b32 m0, s80
	v_lshl_add_u64 v[212:213], v[212:213], 0, s[10:11]
	s_add_u32 s48, s48, 0x100080
	ds_read_b128 v[180:183], v159 offset:49152
	ds_read_b128 v[184:187], v159 offset:50176
	ds_read_b128 v[188:191], v159 offset:51200
	ds_read_b128 v[192:195], v159 offset:52224
	ds_read_b128 v[196:199], v159 offset:53248
	ds_read_b128 v[200:203], v159 offset:54272
	ds_read_b128 v[204:207], v159 offset:55296
	ds_read_b128 v[208:211], v159 offset:56320
	global_load_lds_dwordx4 v[212:213], off
	v_lshl_add_u64 v[212:213], v[214:215], 0, s[10:11]
	s_mov_b32 m0, s81
	s_addc_u32 s49, s49, 0
	global_load_lds_dwordx4 v[212:213], off
	v_lshl_add_u64 v[212:213], s[48:49], 0, v[132:133]
	s_mov_b32 m0, s82
	s_nop 0
	global_load_lds_dwordx4 v[212:213], off
	v_lshl_add_u64 v[212:213], s[48:49], 0, v[128:129]
	s_mov_b32 m0, s83
	s_nop 0
	global_load_lds_dwordx4 v[212:213], off
	v_lshl_add_u64 v[212:213], v[216:217], 0, s[10:11]
	s_mov_b32 m0, s64
	s_nop 0
	global_load_lds_dwordx4 v[212:213], off
	v_lshl_add_u64 v[212:213], v[218:219], 0, s[10:11]
	s_mov_b32 m0, s65
	s_nop 0
	global_load_lds_dwordx4 v[212:213], off
	s_waitcnt vmcnt(8)
	s_waitcnt lgkmcnt(0)
	s_barrier
	v_mfma_f32_16x16x32_bf16 v[76:79], v[144:147], v[180:183], v[76:79]
	v_mfma_f32_16x16x32_bf16 v[76:79], v[148:151], v[184:187], v[76:79]
	v_mfma_f32_16x16x32_bf16 v[72:75], v[160:163], v[184:187], v[72:75]
	v_mfma_f32_16x16x32_bf16 v[72:75], v[152:155], v[180:183], v[72:75]
	v_mfma_f32_16x16x32_bf16 v[40:43], v[152:155], v[188:191], v[40:43]
	v_mfma_f32_16x16x32_bf16 v[40:43], v[160:163], v[192:195], v[40:43]
	v_mfma_f32_16x16x32_bf16 v[44:47], v[148:151], v[192:195], v[44:47]
	v_mfma_f32_16x16x32_bf16 v[44:47], v[144:147], v[188:191], v[44:47]
	v_mfma_f32_16x16x32_bf16 v[28:31], v[144:147], v[196:199], v[28:31]
	v_mfma_f32_16x16x32_bf16 v[28:31], v[148:151], v[200:203], v[28:31]
	v_mfma_f32_16x16x32_bf16 v[24:27], v[160:163], v[200:203], v[24:27]
	v_mfma_f32_16x16x32_bf16 v[24:27], v[152:155], v[196:199], v[24:27]
	v_mfma_f32_16x16x32_bf16 v[8:11], v[152:155], v[204:207], v[8:11]
	v_mfma_f32_16x16x32_bf16 v[8:11], v[160:163], v[208:211], v[8:11]
	v_mfma_f32_16x16x32_bf16 v[12:15], v[148:151], v[208:211], v[12:15]
	v_mfma_f32_16x16x32_bf16 v[12:15], v[144:147], v[204:207], v[12:15]
	v_mfma_f32_16x16x32_bf16 v[68:71], v[164:167], v[180:183], v[68:71]
	v_mfma_f32_16x16x32_bf16 v[68:71], v[168:171], v[184:187], v[68:71]
	v_mfma_f32_16x16x32_bf16 v[60:63], v[176:179], v[184:187], v[60:63]
	v_mfma_f32_16x16x32_bf16 v[60:63], v[172:175], v[180:183], v[60:63]
	v_mfma_f32_16x16x32_bf16 v[32:35], v[172:175], v[188:191], v[32:35]
	v_mfma_f32_16x16x32_bf16 v[32:35], v[176:179], v[192:195], v[32:35]
	v_mfma_f32_16x16x32_bf16 v[36:39], v[168:171], v[192:195], v[36:39]
	v_mfma_f32_16x16x32_bf16 v[36:39], v[164:167], v[188:191], v[36:39]
	v_mfma_f32_16x16x32_bf16 v[20:23], v[164:167], v[196:199], v[20:23]
	v_mfma_f32_16x16x32_bf16 v[20:23], v[168:171], v[200:203], v[20:23]
	v_mfma_f32_16x16x32_bf16 v[16:19], v[176:179], v[200:203], v[16:19]
	v_mfma_f32_16x16x32_bf16 v[16:19], v[172:175], v[196:199], v[16:19]
	v_mfma_f32_16x16x32_bf16 v[0:3], v[172:175], v[204:207], v[0:3]
	v_mfma_f32_16x16x32_bf16 v[0:3], v[176:179], v[208:211], v[0:3]
	v_mfma_f32_16x16x32_bf16 v[4:7], v[168:171], v[208:211], v[4:7]
	v_mfma_f32_16x16x32_bf16 v[4:7], v[164:167], v[204:207], v[4:7]
	s_barrier
	s_add_i32 s86, s86, 2
	s_add_u32 s46, s46, 0x100
	s_addc_u32 s47, s47, 0
	s_add_u32 s84, s84, 0x100
	s_addc_u32 s85, s85, 0
	s_cmp_gt_u32 s86, 61
	s_cbranch_scc0 .LBB0_41
	s_and_b64 vcc, exec, s[14:15]
	s_cbranch_vccz .LBB0_44
	s_barrier

; #define PG8_LAS __attribute__((address_space(3)))
; #define PG8_STAGE(bufoff, gbase, voff) do { _Pragma("unroll") for (int _i = 0; _i < 2; ++_i) \
;         __builtin_amdgcn_global_load_lds((const unsigned*)((const char*)(gbase) + (voff)[_i]), (PG8_LAS unsigned*)(lds + (bufoff) + ldsw + _i * 8192), 16, 0, 0); } while (0)
; #define PG8_LDA(dst, b, h) do { _Pragma("unroll") for (int m = 0; m < 4; ++m) _Pragma("unroll") for (int k = 0; k < 2; ++k) dst[m][k] = *(const PG8_LAS bf16x8*)(lds + PG8_SA(b, h) + aoff + m * 2048 + k * 1024); } while (0)
; #define PG8_LDB(dst, b, h) do { _Pragma("unroll") for (int n = 0; n < 2; ++n) _Pragma("unroll") for (int k = 0; k < 2; ++k) dst[n][k] = *(const PG8_LAS bf16x8*)(lds + PG8_SB(b, h) + boff + n * 2048 + k * 1024); } while (0)
; #define PG8_WAIT_V(n) asm volatile("s_waitcnt vmcnt(" #n ")" ::: "memory")
; #define PG8_WAIT_L(n) asm volatile("s_waitcnt lgkmcnt(" #n ")" ::: "memory")
; #define PG8_BAR __builtin_amdgcn_s_barrier()
; #define PG8_SCHED __builtin_amdgcn_sched_barrier(0)
; template <class Epi, class Sched, bool ALIGN_EPI = false, bool SP2 = false>
; __device__ __forceinline__ void gemm_phase(PG8_LAS unsigned char* lds, const Gemm g, const Sched& S, const Epi& E, int wave_s) {
;     ...
;         for (int t = 0; t < nt; t += 2) {
;             const bool last = (t == nt - 2);
;             if constexpr (Epi::NEED_RS) { if (t == 0 && wid < 4) __builtin_amdgcn_global_load_lds((const unsigned*)(E.rstd + cur.pm * BM + wid * 64 + lane), (PG8_LAS unsigned*)(rsl + wid * 64), 4, 0, 0); }
;             const char* a1 = cA + (size_t)(t + 1) * kstep;
;             const char* a2 = last ? nA : cA + (size_t)(t + 2) * kstep; const char* b2 = last ? nB : cB + (size_t)(t + 2) * kstep;
;             const char* a3 = a2 + kstep; const char* b3 = b2 + kstep;
;             if (last && has_next) S.a_ready(nxt);
;             if constexpr (SP2) {
;             PG8_LDB(B0, 0, 0); PG8_LDB(B1, 0, 1); PG8_SCHED; PG8_LDA(At, 0, 0); PG8_STAGE(PG8_SA(1, 1), a1 + hstep, voffA);
;             PG8_WAIT_V(8); PG8_WAIT_L(0); PG8_BAR; PG8_MMA(0, 0, At, B0); PG8_MMA(0, 1, At, B1); PG8_BAR; PG8_SCHED;
;             PG8_LDA(At, 0, 1); PG8_STAGE(PG8_SB(0, 0), b2, voffB); PG8_STAGE(PG8_SB(0, 1), b2 + hstep, voffB); PG8_STAGE(PG8_SA(0, 0), a2, voffA);
.LBB0_1200:
	ds_read_b128 v[128:131], v211
	ds_read_b128 v[132:135], v211 offset:1024
	ds_read_b128 v[136:139], v211 offset:2048
	ds_read_b128 v[140:143], v211 offset:3072
	ds_read_b128 v[144:147], v212
	ds_read_b128 v[148:151], v212 offset:1024
	ds_read_b128 v[152:155], v212 offset:2048
	ds_read_b128 v[156:159], v212 offset:3072
	s_add_u32 s45, s50, 0xfff00080
	s_addc_u32 s52, s51, -1
	s_cmp_eq_u32 s85, s43
	s_cselect_b32 s55, s47, s52
	s_cselect_b32 s54, s46, s45
	s_cselect_b32 s53, s49, s41
	s_cselect_b32 s52, s48, s7
	v_lshl_add_u64 v[204:205], s[50:51], 0, v[192:193]
	s_add_i32 m0, s9, 0xc000
	ds_read_b128 v[160:163], v213
	ds_read_b128 v[164:167], v213 offset:1024
	ds_read_b128 v[168:171], v213 offset:2048
	ds_read_b128 v[172:175], v213 offset:3072
	ds_read_b128 v[176:179], v213 offset:4096
	ds_read_b128 v[180:183], v213 offset:5120
	ds_read_b128 v[196:199], v213 offset:6144
	ds_read_b128 v[200:203], v213 offset:7168
	global_load_lds_dwordx4 v[204:205], off
	v_lshl_add_u64 v[204:205], s[50:51], 0, v[194:195]
	s_add_i32 m0, s9, 0xe000
	s_nop 0
	global_load_lds_dwordx4 v[204:205], off
	s_waitcnt vmcnt(8)
	s_waitcnt lgkmcnt(0)
	s_barrier
	v_mfma_f32_16x16x32_bf16 v[124:127], v[128:131], v[160:163], v[124:127]
	v_mfma_f32_16x16x32_bf16 v[124:127], v[132:135], v[164:167], v[124:127]
	v_mfma_f32_16x16x32_bf16 v[120:123], v[140:143], v[164:167], v[120:123]
	v_mfma_f32_16x16x32_bf16 v[120:123], v[136:139], v[160:163], v[120:123]
	v_mfma_f32_16x16x32_bf16 v[104:107], v[136:139], v[168:171], v[104:107]
	v_mfma_f32_16x16x32_bf16 v[104:107], v[140:143], v[172:175], v[104:107]
	v_mfma_f32_16x16x32_bf16 v[108:111], v[132:135], v[172:175], v[108:111]
	v_mfma_f32_16x16x32_bf16 v[108:111], v[128:131], v[168:171], v[108:111]
	v_mfma_f32_16x16x32_bf16 v[92:95], v[128:131], v[176:179], v[92:95]
	v_mfma_f32_16x16x32_bf16 v[92:95], v[132:135], v[180:183], v[92:95]
	v_mfma_f32_16x16x32_bf16 v[88:91], v[140:143], v[180:183], v[88:91]
	v_mfma_f32_16x16x32_bf16 v[88:91], v[136:139], v[176:179], v[88:91]
	v_mfma_f32_16x16x32_bf16 v[72:75], v[136:139], v[196:199], v[72:75]
	v_mfma_f32_16x16x32_bf16 v[72:75], v[140:143], v[200:203], v[72:75]
	v_mfma_f32_16x16x32_bf16 v[76:79], v[132:135], v[200:203], v[76:79]
	v_mfma_f32_16x16x32_bf16 v[76:79], v[128:131], v[196:199], v[76:79]
	v_mfma_f32_16x16x32_bf16 v[116:119], v[144:147], v[160:163], v[116:119]
	v_mfma_f32_16x16x32_bf16 v[116:119], v[148:151], v[164:167], v[116:119]
	v_mfma_f32_16x16x32_bf16 v[112:115], v[156:159], v[164:167], v[112:115]
	v_mfma_f32_16x16x32_bf16 v[112:115], v[152:155], v[160:163], v[112:115]
	v_mfma_f32_16x16x32_bf16 v[96:99], v[152:155], v[168:171], v[96:99]
	v_mfma_f32_16x16x32_bf16 v[96:99], v[156:159], v[172:175], v[96:99]
	v_mfma_f32_16x16x32_bf16 v[100:103], v[148:151], v[172:175], v[100:103]
	v_mfma_f32_16x16x32_bf16 v[100:103], v[144:147], v[168:171], v[100:103]
	v_mfma_f32_16x16x32_bf16 v[84:87], v[144:147], v[176:179], v[84:87]
	v_mfma_f32_16x16x32_bf16 v[84:87], v[148:151], v[180:183], v[84:87]
	v_mfma_f32_16x16x32_bf16 v[80:83], v[156:159], v[180:183], v[80:83]
	v_mfma_f32_16x16x32_bf16 v[80:83], v[152:155], v[176:179], v[80:83]
	v_mfma_f32_16x16x32_bf16 v[64:67], v[152:155], v[196:199], v[64:67]
	v_mfma_f32_16x16x32_bf16 v[64:67], v[156:159], v[200:203], v[64:67]
	v_mfma_f32_16x16x32_bf16 v[68:71], v[148:151], v[200:203], v[68:71]
	v_mfma_f32_16x16x32_bf16 v[68:71], v[144:147], v[196:199], v[68:71]
	s_barrier
	s_add_i32 s45, s75, s60
	v_lshl_add_u64 v[204:205], s[52:53], 0, v[186:187]
	s_mov_b32 m0, s45
	ds_read_b128 v[160:163], v213 offset:16384
	ds_read_b128 v[164:167], v213 offset:17408
	ds_read_b128 v[168:171], v213 offset:18432
	ds_read_b128 v[172:175], v213 offset:19456
	ds_read_b128 v[176:179], v213 offset:20480
	ds_read_b128 v[180:183], v213 offset:21504
	ds_read_b128 v[196:199], v213 offset:22528
	ds_read_b128 v[200:203], v213 offset:23552
	global_load_lds_dwordx4 v[204:205], off
	s_add_i32 m0, s45, 0x2000
	s_add_u32 s86, s52, 0x100000
	v_lshl_add_u64 v[206:207], s[52:53], 0, v[190:191]
	s_addc_u32 s87, s53, 0
	s_add_i32 s45, s76, s60
	global_load_lds_dwordx4 v[206:207], off
	v_lshl_add_u64 v[208:209], s[86:87], 0, v[186:187]
	s_mov_b32 m0, s45
	v_lshl_add_u64 v[216:217], s[54:55], 0, v[188:189]
	global_load_lds_dwordx4 v[208:209], off
	v_lshl_add_u64 v[208:209], s[86:87], 0, v[190:191]
	s_add_i32 m0, s45, 0x2000
	s_nop 0
	global_load_lds_dwordx4 v[208:209], off
	v_lshl_add_u64 v[208:209], s[54:55], 0, v[184:185]
	s_mov_b32 m0, s9
	s_nop 0
	global_load_lds_dwordx4 v[208:209], off
	s_mov_b32 m0, s61
	s_nop 0
	global_load_lds_dwordx4 v[216:217], off
	s_waitcnt vmcnt(8)
	s_waitcnt lgkmcnt(0)
	s_barrier
; #define PG8_STAGE(bufoff, gbase, voff) do { _Pragma("unroll") for (int _i = 0; _i < 2; ++_i) \
;         __builtin_amdgcn_global_load_lds((const unsigned*)((const char*)(gbase) + (voff)[_i]), (PG8_LAS unsigned*)(lds + (bufoff) + ldsw + _i * 8192), 16, 0, 0); } while (0)
; #define PG8_LDA(dst, b, h) do { _Pragma("unroll") for (int m = 0; m < 4; ++m) _Pragma("unroll") for (int k = 0; k < 2; ++k) dst[m][k] = *(const PG8_LAS bf16x8*)(lds + PG8_SA(b, h) + aoff + m * 2048 + k * 1024); } while (0)
; #define PG8_LDB(dst, b, h) do { _Pragma("unroll") for (int n = 0; n < 2; ++n) _Pragma("unroll") for (int k = 0; k < 2; ++k) dst[n][k] = *(const PG8_LAS bf16x8*)(lds + PG8_SB(b, h) + boff + n * 2048 + k * 1024); } while (0)
; #define PG8_MMA(ai, bj, At, Bt) do { __builtin_amdgcn_s_setprio(1); _Pragma("unroll") for (int m = 0; m < 4; ++m) _Pragma("unroll") for (int n = 0; n < 2; ++n) _Pragma("unroll") for (int k = 0; k < 2; ++k) \
;         acc[ai][bj][m][n] = __builtin_amdgcn_mfma_f32_16x16x32_bf16(Bt[n][k], At[m][k], acc[ai][bj][m][n], 0, 0, 0); __builtin_amdgcn_s_setprio(0); } while (0)
; #define PG8_WAIT_V(n) asm volatile("s_waitcnt vmcnt(" #n ")" ::: "memory")
; #define PG8_WAIT_L(n) asm volatile("s_waitcnt lgkmcnt(" #n ")" ::: "memory")
; #define PG8_BAR __builtin_amdgcn_s_barrier()
; #define PG8_SCHED __builtin_amdgcn_sched_barrier(0)
; template <class Epi, class Sched, bool ALIGN_EPI = false, bool SP2 = false>
; __device__ __forceinline__ void gemm_phase(PG8_LAS unsigned char* lds, const Gemm g, const Sched& S, const Epi& E, int wave_s) {
;     ...
;             PG8_WAIT_V(8); PG8_WAIT_L(0); PG8_BAR; PG8_MMA(1, 0, At, B0); PG8_MMA(1, 1, At, B1); PG8_BAR; PG8_SCHED;
;             PG8_LDB(B0, 1, 0); PG8_LDB(B1, 1, 1); PG8_SCHED; PG8_LDA(At, 1, 0); PG8_STAGE(PG8_SA(0, 1), a2 + hstep, voffA);
;             PG8_WAIT_V(8); PG8_WAIT_L(0); PG8_BAR; PG8_MMA(0, 0, At, B0); PG8_MMA(0, 1, At, B1); PG8_BAR; PG8_SCHED;
	v_mfma_f32_16x16x32_bf16 v[60:63], v[128:131], v[160:163], v[60:63]
	v_mfma_f32_16x16x32_bf16 v[60:63], v[132:135], v[164:167], v[60:63]
	v_mfma_f32_16x16x32_bf16 v[56:59], v[140:143], v[164:167], v[56:59]
	v_mfma_f32_16x16x32_bf16 v[56:59], v[136:139], v[160:163], v[56:59]
	v_mfma_f32_16x16x32_bf16 v[40:43], v[136:139], v[168:171], v[40:43]
	v_mfma_f32_16x16x32_bf16 v[40:43], v[140:143], v[172:175], v[40:43]
	v_mfma_f32_16x16x32_bf16 v[44:47], v[132:135], v[172:175], v[44:47]
	v_mfma_f32_16x16x32_bf16 v[44:47], v[128:131], v[168:171], v[44:47]
	v_mfma_f32_16x16x32_bf16 v[28:31], v[128:131], v[176:179], v[28:31]
	v_mfma_f32_16x16x32_bf16 v[28:31], v[132:135], v[180:183], v[28:31]
	v_mfma_f32_16x16x32_bf16 v[24:27], v[140:143], v[180:183], v[24:27]
	v_mfma_f32_16x16x32_bf16 v[24:27], v[136:139], v[176:179], v[24:27]
	v_mfma_f32_16x16x32_bf16 v[8:11], v[136:139], v[196:199], v[8:11]
	v_mfma_f32_16x16x32_bf16 v[8:11], v[140:143], v[200:203], v[8:11]
	v_mfma_f32_16x16x32_bf16 v[12:15], v[132:135], v[200:203], v[12:15]
	v_mfma_f32_16x16x32_bf16 v[12:15], v[128:131], v[196:199], v[12:15]
	v_mfma_f32_16x16x32_bf16 v[52:55], v[144:147], v[160:163], v[52:55]
	v_mfma_f32_16x16x32_bf16 v[52:55], v[148:151], v[164:167], v[52:55]
	v_mfma_f32_16x16x32_bf16 v[48:51], v[156:159], v[164:167], v[48:51]
	v_mfma_f32_16x16x32_bf16 v[48:51], v[152:155], v[160:163], v[48:51]
	v_mfma_f32_16x16x32_bf16 v[32:35], v[152:155], v[168:171], v[32:35]
	v_mfma_f32_16x16x32_bf16 v[32:35], v[156:159], v[172:175], v[32:35]
	v_mfma_f32_16x16x32_bf16 v[36:39], v[148:151], v[172:175], v[36:39]
	v_mfma_f32_16x16x32_bf16 v[36:39], v[144:147], v[168:171], v[36:39]
	v_mfma_f32_16x16x32_bf16 v[20:23], v[144:147], v[176:179], v[20:23]
	v_mfma_f32_16x16x32_bf16 v[20:23], v[148:151], v[180:183], v[20:23]
	v_mfma_f32_16x16x32_bf16 v[16:19], v[156:159], v[180:183], v[16:19]
	v_mfma_f32_16x16x32_bf16 v[16:19], v[152:155], v[176:179], v[16:19]
	v_mfma_f32_16x16x32_bf16 v[0:3], v[152:155], v[196:199], v[0:3]
	v_mfma_f32_16x16x32_bf16 v[0:3], v[156:159], v[200:203], v[0:3]
	v_mfma_f32_16x16x32_bf16 v[4:7], v[148:151], v[200:203], v[4:7]
	v_mfma_f32_16x16x32_bf16 v[4:7], v[144:147], v[196:199], v[4:7]
	s_barrier
	s_add_i32 s45, 0, 0x18000
	s_add_i32 s86, 0, 0x1c000
	v_add_u32_e32 v140, s45, v210
	v_add_u32_e32 v156, s86, v210
	ds_read_b128 v[128:131], v140
	ds_read_b128 v[132:135], v140 offset:1024
	ds_read_b128 v[136:139], v140 offset:2048
	ds_read_b128 v[140:143], v140 offset:3072
	ds_read_b128 v[144:147], v156
	ds_read_b128 v[148:151], v156 offset:1024
	ds_read_b128 v[152:155], v156 offset:2048
	ds_read_b128 v[156:159], v156 offset:3072
	s_add_u32 s54, s54, 0x100000
	s_addc_u32 s55, s55, 0
	s_mov_b32 m0, s62
	v_lshl_add_u64 v[218:219], s[54:55], 0, v[184:185]
	ds_read_b128 v[160:163], v213 offset:32768
	ds_read_b128 v[164:167], v213 offset:33792
	ds_read_b128 v[168:171], v213 offset:34816
	ds_read_b128 v[172:175], v213 offset:35840
	ds_read_b128 v[176:179], v213 offset:36864
	ds_read_b128 v[180:183], v213 offset:37888
	ds_read_b128 v[196:199], v213 offset:38912
	ds_read_b128 v[200:203], v213 offset:39936
	global_load_lds_dwordx4 v[218:219], off
	v_lshl_add_u64 v[218:219], s[54:55], 0, v[188:189]
	s_mov_b32 m0, s63
	s_nop 0
	global_load_lds_dwordx4 v[218:219], off
	s_waitcnt vmcnt(8)
	s_waitcnt lgkmcnt(0)
	s_barrier
	v_mfma_f32_16x16x32_bf16 v[124:127], v[128:131], v[160:163], v[124:127]
	v_mfma_f32_16x16x32_bf16 v[124:127], v[132:135], v[164:167], v[124:127]
	v_mfma_f32_16x16x32_bf16 v[120:123], v[140:143], v[164:167], v[120:123]
	v_mfma_f32_16x16x32_bf16 v[120:123], v[136:139], v[160:163], v[120:123]
	v_mfma_f32_16x16x32_bf16 v[104:107], v[136:139], v[168:171], v[104:107]
	v_mfma_f32_16x16x32_bf16 v[104:107], v[140:143], v[172:175], v[104:107]
	v_mfma_f32_16x16x32_bf16 v[108:111], v[132:135], v[172:175], v[108:111]
	v_mfma_f32_16x16x32_bf16 v[108:111], v[128:131], v[168:171], v[108:111]
	v_mfma_f32_16x16x32_bf16 v[92:95], v[128:131], v[176:179], v[92:95]
	v_mfma_f32_16x16x32_bf16 v[92:95], v[132:135], v[180:183], v[92:95]
	v_mfma_f32_16x16x32_bf16 v[88:91], v[140:143], v[180:183], v[88:91]
	v_mfma_f32_16x16x32_bf16 v[88:91], v[136:139], v[176:179], v[88:91]
	v_mfma_f32_16x16x32_bf16 v[72:75], v[136:139], v[196:199], v[72:75]
	v_mfma_f32_16x16x32_bf16 v[72:75], v[140:143], v[200:203], v[72:75]
	v_mfma_f32_16x16x32_bf16 v[76:79], v[132:135], v[200:203], v[76:79]
	v_mfma_f32_16x16x32_bf16 v[76:79], v[128:131], v[196:199], v[76:79]
	v_mfma_f32_16x16x32_bf16 v[116:119], v[144:147], v[160:163], v[116:119]
	v_mfma_f32_16x16x32_bf16 v[116:119], v[148:151], v[164:167], v[116:119]
	v_mfma_f32_16x16x32_bf16 v[112:115], v[156:159], v[164:167], v[112:115]
	v_mfma_f32_16x16x32_bf16 v[112:115], v[152:155], v[160:163], v[112:115]
	v_mfma_f32_16x16x32_bf16 v[96:99], v[152:155], v[168:171], v[96:99]
	v_mfma_f32_16x16x32_bf16 v[96:99], v[156:159], v[172:175], v[96:99]
	v_mfma_f32_16x16x32_bf16 v[100:103], v[148:151], v[172:175], v[100:103]
	v_mfma_f32_16x16x32_bf16 v[100:103], v[144:147], v[168:171], v[100:103]
	v_mfma_f32_16x16x32_bf16 v[84:87], v[144:147], v[176:179], v[84:87]
	v_mfma_f32_16x16x32_bf16 v[84:87], v[148:151], v[180:183], v[84:87]
	v_mfma_f32_16x16x32_bf16 v[80:83], v[156:159], v[180:183], v[80:83]
	v_mfma_f32_16x16x32_bf16 v[80:83], v[152:155], v[176:179], v[80:83]
	v_mfma_f32_16x16x32_bf16 v[64:67], v[152:155], v[196:199], v[64:67]
	v_mfma_f32_16x16x32_bf16 v[64:67], v[156:159], v[200:203], v[64:67]
	v_mfma_f32_16x16x32_bf16 v[68:71], v[148:151], v[200:203], v[68:71]
	v_mfma_f32_16x16x32_bf16 v[68:71], v[144:147], v[196:199], v[68:71]
	s_barrier
; #define PG8_STAGE(bufoff, gbase, voff) do { _Pragma("unroll") for (int _i = 0; _i < 2; ++_i) \
;         __builtin_amdgcn_global_load_lds((const unsigned*)((const char*)(gbase) + (voff)[_i]), (PG8_LAS unsigned*)(lds + (bufoff) + ldsw + _i * 8192), 16, 0, 0); } while (0)
; #define PG8_LDA(dst, b, h) do { _Pragma("unroll") for (int m = 0; m < 4; ++m) _Pragma("unroll") for (int k = 0; k < 2; ++k) dst[m][k] = *(const PG8_LAS bf16x8*)(lds + PG8_SA(b, h) + aoff + m * 2048 + k * 1024); } while (0)
; #define PG8_MMA(ai, bj, At, Bt) do { __builtin_amdgcn_s_setprio(1); _Pragma("unroll") for (int m = 0; m < 4; ++m) _Pragma("unroll") for (int n = 0; n < 2; ++n) _Pragma("unroll") for (int k = 0; k < 2; ++k) \
;         acc[ai][bj][m][n] = __builtin_amdgcn_mfma_f32_16x16x32_bf16(Bt[n][k], At[m][k], acc[ai][bj][m][n], 0, 0, 0); __builtin_amdgcn_s_setprio(0); } while (0)
; #define PG8_WAIT_V(n) asm volatile("s_waitcnt vmcnt(" #n ")" ::: "memory")
; #define PG8_WAIT_L(n) asm volatile("s_waitcnt lgkmcnt(" #n ")" ::: "memory")
; #define PG8_BAR __builtin_amdgcn_s_barrier()
; #define PG8_SCHED __builtin_amdgcn_sched_barrier(0)
; template <class Epi, class Sched, bool ALIGN_EPI = false, bool SP2 = false>
; __device__ __forceinline__ void gemm_phase(PG8_LAS unsigned char* lds, const Gemm g, const Sched& S, const Epi& E, int wave_s) {
;     ...
;             PG8_LDA(At, 1, 1); PG8_STAGE(PG8_SB(1, 0), b3, voffB); PG8_STAGE(PG8_SB(1, 1), b3 + hstep, voffB); PG8_STAGE(PG8_SA(1, 0), a3, voffA);
;             PG8_WAIT_V(8); PG8_WAIT_L(0); PG8_BAR; PG8_MMA(1, 0, At, B0); PG8_MMA(1, 1, At, B1); PG8_BAR; PG8_SCHED;
;     ...
;         if constexpr (ALIGN_EPI) { if (wr == 0) PG8_BAR; }
	s_add_i32 s45, s45, s60
	v_lshl_add_u64 v[204:205], v[204:205], 0, s[18:19]
	s_mov_b32 m0, s45
	ds_read_b128 v[160:163], v213 offset:49152
	ds_read_b128 v[164:167], v213 offset:50176
	ds_read_b128 v[168:171], v213 offset:51200
	ds_read_b128 v[172:175], v213 offset:52224
	ds_read_b128 v[176:179], v213 offset:53248
	ds_read_b128 v[180:183], v213 offset:54272
	ds_read_b128 v[196:199], v213 offset:55296
	ds_read_b128 v[200:203], v213 offset:56320
	global_load_lds_dwordx4 v[204:205], off
	s_add_i32 m0, s45, 0x2000
	s_add_u32 s52, s52, 0x100080
	v_lshl_add_u64 v[204:205], v[206:207], 0, s[18:19]
	s_addc_u32 s53, s53, 0
	s_add_i32 s45, s86, s60
	global_load_lds_dwordx4 v[204:205], off
	v_lshl_add_u64 v[204:205], s[52:53], 0, v[186:187]
	s_mov_b32 m0, s45
	s_nop 0
	global_load_lds_dwordx4 v[204:205], off
	v_lshl_add_u64 v[204:205], s[52:53], 0, v[190:191]
	s_add_i32 m0, s45, 0x2000
	s_nop 0
	global_load_lds_dwordx4 v[204:205], off
	v_lshl_add_u64 v[204:205], v[208:209], 0, s[18:19]
	s_mov_b32 m0, s70
	s_nop 0
	global_load_lds_dwordx4 v[204:205], off
	v_lshl_add_u64 v[204:205], v[216:217], 0, s[18:19]
	s_mov_b32 m0, s71
	s_nop 0
	global_load_lds_dwordx4 v[204:205], off
	s_waitcnt vmcnt(8)
	s_waitcnt lgkmcnt(0)
	s_barrier
	v_mfma_f32_16x16x32_bf16 v[60:63], v[128:131], v[160:163], v[60:63]
	v_mfma_f32_16x16x32_bf16 v[60:63], v[132:135], v[164:167], v[60:63]
	v_mfma_f32_16x16x32_bf16 v[56:59], v[140:143], v[164:167], v[56:59]
	v_mfma_f32_16x16x32_bf16 v[56:59], v[136:139], v[160:163], v[56:59]
	v_mfma_f32_16x16x32_bf16 v[40:43], v[136:139], v[168:171], v[40:43]
	v_mfma_f32_16x16x32_bf16 v[40:43], v[140:143], v[172:175], v[40:43]
	v_mfma_f32_16x16x32_bf16 v[44:47], v[132:135], v[172:175], v[44:47]
	v_mfma_f32_16x16x32_bf16 v[44:47], v[128:131], v[168:171], v[44:47]
	v_mfma_f32_16x16x32_bf16 v[28:31], v[128:131], v[176:179], v[28:31]
	v_mfma_f32_16x16x32_bf16 v[28:31], v[132:135], v[180:183], v[28:31]
	v_mfma_f32_16x16x32_bf16 v[24:27], v[140:143], v[180:183], v[24:27]
	v_mfma_f32_16x16x32_bf16 v[24:27], v[136:139], v[176:179], v[24:27]
	v_mfma_f32_16x16x32_bf16 v[8:11], v[136:139], v[196:199], v[8:11]
	v_mfma_f32_16x16x32_bf16 v[8:11], v[140:143], v[200:203], v[8:11]
	v_mfma_f32_16x16x32_bf16 v[12:15], v[132:135], v[200:203], v[12:15]
	v_mfma_f32_16x16x32_bf16 v[12:15], v[128:131], v[196:199], v[12:15]
	v_mfma_f32_16x16x32_bf16 v[52:55], v[144:147], v[160:163], v[52:55]
	v_mfma_f32_16x16x32_bf16 v[52:55], v[148:151], v[164:167], v[52:55]
	v_mfma_f32_16x16x32_bf16 v[48:51], v[156:159], v[164:167], v[48:51]
	v_mfma_f32_16x16x32_bf16 v[48:51], v[152:155], v[160:163], v[48:51]
	v_mfma_f32_16x16x32_bf16 v[32:35], v[152:155], v[168:171], v[32:35]
	v_mfma_f32_16x16x32_bf16 v[32:35], v[156:159], v[172:175], v[32:35]
	v_mfma_f32_16x16x32_bf16 v[36:39], v[148:151], v[172:175], v[36:39]
	v_mfma_f32_16x16x32_bf16 v[36:39], v[144:147], v[168:171], v[36:39]
	v_mfma_f32_16x16x32_bf16 v[20:23], v[144:147], v[176:179], v[20:23]
	v_mfma_f32_16x16x32_bf16 v[20:23], v[148:151], v[180:183], v[20:23]
	v_mfma_f32_16x16x32_bf16 v[16:19], v[156:159], v[180:183], v[16:19]
	v_mfma_f32_16x16x32_bf16 v[16:19], v[152:155], v[176:179], v[16:19]
	v_mfma_f32_16x16x32_bf16 v[0:3], v[152:155], v[196:199], v[0:3]
	v_mfma_f32_16x16x32_bf16 v[0:3], v[156:159], v[200:203], v[0:3]
	v_mfma_f32_16x16x32_bf16 v[4:7], v[148:151], v[200:203], v[4:7]
	v_mfma_f32_16x16x32_bf16 v[4:7], v[144:147], v[196:199], v[4:7]
	s_barrier
	s_add_i32 s45, s43, 2
	s_add_u32 s50, s50, 0x100
	s_addc_u32 s51, s51, 0
	s_add_u32 s7, s7, 0x100
	s_addc_u32 s41, s41, 0
	s_cmp_ge_i32 s43, s85
	s_mov_b32 s43, s45
	s_cbranch_scc0 .LBB0_1200
	s_and_b64 vcc, exec, s[20:21]
	s_cbranch_vccz .LBB0_1203
	s_barrier

; #define PG8_LAS __attribute__((address_space(3)))
; #define PG8_STAGE(bufoff, gbase, voff) do { _Pragma("unroll") for (int _i = 0; _i < 2; ++_i) \
;         __builtin_amdgcn_global_load_lds((const unsigned*)((const char*)(gbase) + (voff)[_i]), (PG8_LAS unsigned*)(lds + (bufoff) + ldsw + _i * 8192), 16, 0, 0); } while (0)
; #define PG8_LDA(dst, b, h) do { _Pragma("unroll") for (int m = 0; m < 4; ++m) _Pragma("unroll") for (int k = 0; k < 2; ++k) dst[m][k] = *(const PG8_LAS bf16x8*)(lds + PG8_SA(b, h) + aoff + m * 2048 + k * 1024); } while (0)
; #define PG8_LDB(dst, b, h) do { _Pragma("unroll") for (int n = 0; n < 2; ++n) _Pragma("unroll") for (int k = 0; k < 2; ++k) dst[n][k] = *(const PG8_LAS bf16x8*)(lds + PG8_SB(b, h) + boff + n * 2048 + k * 1024); } while (0)
; #define PG8_WAIT_V(n) asm volatile("s_waitcnt vmcnt(" #n ")" ::: "memory")
; #define PG8_WAIT_L(n) asm volatile("s_waitcnt lgkmcnt(" #n ")" ::: "memory")
; #define PG8_BAR __builtin_amdgcn_s_barrier()
; #define PG8_SCHED __builtin_amdgcn_sched_barrier(0)
; template <class Epi, class Sched, bool ALIGN_EPI = false, bool SP2 = false>
; __device__ __forceinline__ void gemm_phase(PG8_LAS unsigned char* lds, const Gemm g, const Sched& S, const Epi& E, int wave_s) {
;     ...
;         for (int t = 0; t < nt; t += 2) {
;             const bool last = (t == nt - 2);
;             if constexpr (Epi::NEED_RS) { if (t == 0 && wid < 4) __builtin_amdgcn_global_load_lds((const unsigned*)(E.rstd + cur.pm * BM + wid * 64 + lane), (PG8_LAS unsigned*)(rsl + wid * 64), 4, 0, 0); }
;             const char* a1 = cA + (size_t)(t + 1) * kstep;
;             const char* a2 = last ? nA : cA + (size_t)(t + 2) * kstep; const char* b2 = last ? nB : cB + (size_t)(t + 2) * kstep;
;             const char* a3 = a2 + kstep; const char* b3 = b2 + kstep;
;             if (last && has_next) S.a_ready(nxt);
;             if constexpr (SP2) {
;             PG8_LDB(B0, 0, 0); PG8_LDB(B1, 0, 1); PG8_SCHED; PG8_LDA(At, 0, 0); PG8_STAGE(PG8_SA(1, 1), a1 + hstep, voffA);
;             PG8_WAIT_V(8); PG8_WAIT_L(0); PG8_BAR; PG8_MMA(0, 0, At, B0); PG8_MMA(0, 1, At, B1); PG8_BAR; PG8_SCHED;
;             PG8_LDA(At, 0, 1); PG8_STAGE(PG8_SB(0, 0), b2, voffB); PG8_STAGE(PG8_SB(0, 1), b2 + hstep, voffB); PG8_STAGE(PG8_SA(0, 0), a2, voffA);
.LBB0_1343:
	ds_read_b128 v[144:147], v150 offset:3072
	ds_read_b128 v[152:155], v150 offset:2048
	ds_read_b128 v[156:159], v150 offset:1024
	ds_read_b128 v[160:163], v150
	ds_read_b128 v[164:167], v149 offset:3072
	ds_read_b128 v[168:171], v149 offset:2048
	ds_read_b128 v[172:175], v149 offset:1024
	ds_read_b128 v[176:179], v149
	s_add_u32 s46, s44, 0xfff00080
	s_addc_u32 s47, s45, -1
	s_cmp_eq_u32 s88, 60
	s_cselect_b32 s49, s29, s47
	s_cselect_b32 s48, s74, s46
	s_cselect_b32 s47, s35, s87
	s_cselect_b32 s46, s75, s86
	s_mov_b32 m0, s76
	v_lshl_add_u64 v[212:213], s[44:45], 0, v[138:139]
	ds_read_b128 v[180:183], v151
	ds_read_b128 v[184:187], v151 offset:1024
	ds_read_b128 v[188:191], v151 offset:2048
	ds_read_b128 v[192:195], v151 offset:3072
	ds_read_b128 v[196:199], v151 offset:4096
	ds_read_b128 v[200:203], v151 offset:5120
	ds_read_b128 v[204:207], v151 offset:6144
	ds_read_b128 v[208:211], v151 offset:7168
	global_load_lds_dwordx4 v[212:213], off
	v_lshl_add_u64 v[212:213], s[44:45], 0, v[140:141]
	s_mov_b32 m0, s77
	s_nop 0
	global_load_lds_dwordx4 v[212:213], off
	s_waitcnt vmcnt(8)
	s_waitcnt lgkmcnt(0)
	s_barrier
	v_mfma_f32_16x16x32_bf16 v[124:127], v[176:179], v[180:183], v[124:127]
	v_mfma_f32_16x16x32_bf16 v[124:127], v[172:175], v[184:187], v[124:127]
	v_mfma_f32_16x16x32_bf16 v[120:123], v[164:167], v[184:187], v[120:123]
	v_mfma_f32_16x16x32_bf16 v[120:123], v[168:171], v[180:183], v[120:123]
	v_mfma_f32_16x16x32_bf16 v[104:107], v[168:171], v[188:191], v[104:107]
	v_mfma_f32_16x16x32_bf16 v[104:107], v[164:167], v[192:195], v[104:107]
	v_mfma_f32_16x16x32_bf16 v[108:111], v[172:175], v[192:195], v[108:111]
	v_mfma_f32_16x16x32_bf16 v[108:111], v[176:179], v[188:191], v[108:111]
	v_mfma_f32_16x16x32_bf16 v[92:95], v[176:179], v[196:199], v[92:95]
	v_mfma_f32_16x16x32_bf16 v[92:95], v[172:175], v[200:203], v[92:95]
	v_mfma_f32_16x16x32_bf16 v[88:91], v[164:167], v[200:203], v[88:91]
	v_mfma_f32_16x16x32_bf16 v[88:91], v[168:171], v[196:199], v[88:91]
	v_mfma_f32_16x16x32_bf16 v[72:75], v[168:171], v[204:207], v[72:75]
	v_mfma_f32_16x16x32_bf16 v[72:75], v[164:167], v[208:211], v[72:75]
	v_mfma_f32_16x16x32_bf16 v[76:79], v[172:175], v[208:211], v[76:79]
	v_mfma_f32_16x16x32_bf16 v[76:79], v[176:179], v[204:207], v[76:79]
	v_mfma_f32_16x16x32_bf16 v[116:119], v[160:163], v[180:183], v[116:119]
	v_mfma_f32_16x16x32_bf16 v[116:119], v[156:159], v[184:187], v[116:119]
	v_mfma_f32_16x16x32_bf16 v[112:115], v[144:147], v[184:187], v[112:115]
	v_mfma_f32_16x16x32_bf16 v[112:115], v[152:155], v[180:183], v[112:115]
	v_mfma_f32_16x16x32_bf16 v[96:99], v[152:155], v[188:191], v[96:99]
	v_mfma_f32_16x16x32_bf16 v[96:99], v[144:147], v[192:195], v[96:99]
	v_mfma_f32_16x16x32_bf16 v[100:103], v[156:159], v[192:195], v[100:103]
	v_mfma_f32_16x16x32_bf16 v[100:103], v[160:163], v[188:191], v[100:103]
	v_mfma_f32_16x16x32_bf16 v[84:87], v[160:163], v[196:199], v[84:87]
	v_mfma_f32_16x16x32_bf16 v[84:87], v[156:159], v[200:203], v[84:87]
	v_mfma_f32_16x16x32_bf16 v[80:83], v[144:147], v[200:203], v[80:83]
	v_mfma_f32_16x16x32_bf16 v[80:83], v[152:155], v[196:199], v[80:83]
	v_mfma_f32_16x16x32_bf16 v[64:67], v[152:155], v[204:207], v[64:67]
	v_mfma_f32_16x16x32_bf16 v[64:67], v[144:147], v[208:211], v[64:67]
	v_mfma_f32_16x16x32_bf16 v[68:71], v[156:159], v[208:211], v[68:71]
	v_mfma_f32_16x16x32_bf16 v[68:71], v[160:163], v[204:207], v[68:71]
	s_barrier
	s_mov_b32 m0, s78
	v_lshl_add_u64 v[212:213], s[46:47], 0, v[132:133]
	s_add_u32 s90, s46, 0x100000
	ds_read_b128 v[180:183], v151 offset:16384
	ds_read_b128 v[184:187], v151 offset:17408
	ds_read_b128 v[188:191], v151 offset:18432
	ds_read_b128 v[192:195], v151 offset:19456
	ds_read_b128 v[196:199], v151 offset:20480
	ds_read_b128 v[200:203], v151 offset:21504
	ds_read_b128 v[204:207], v151 offset:22528
	ds_read_b128 v[208:211], v151 offset:23552
	global_load_lds_dwordx4 v[212:213], off
	v_lshl_add_u64 v[214:215], s[46:47], 0, v[128:129]
	s_mov_b32 m0, s79
	s_addc_u32 s91, s47, 0
	global_load_lds_dwordx4 v[214:215], off
	v_lshl_add_u64 v[216:217], s[90:91], 0, v[132:133]
	s_mov_b32 m0, s80
	v_lshl_add_u64 v[218:219], s[48:49], 0, v[130:131]
	global_load_lds_dwordx4 v[216:217], off
	v_lshl_add_u64 v[216:217], s[90:91], 0, v[128:129]
	s_mov_b32 m0, s81
	s_nop 0
	global_load_lds_dwordx4 v[216:217], off
	v_lshl_add_u64 v[216:217], s[48:49], 0, v[134:135]
	s_mov_b32 m0, s41
	s_nop 0
	global_load_lds_dwordx4 v[216:217], off
	s_mov_b32 m0, s43
	s_nop 0
	global_load_lds_dwordx4 v[218:219], off
	s_waitcnt vmcnt(8)
	s_waitcnt lgkmcnt(0)
	s_barrier
; #define PG8_STAGE(bufoff, gbase, voff) do { _Pragma("unroll") for (int _i = 0; _i < 2; ++_i) \
;         __builtin_amdgcn_global_load_lds((const unsigned*)((const char*)(gbase) + (voff)[_i]), (PG8_LAS unsigned*)(lds + (bufoff) + ldsw + _i * 8192), 16, 0, 0); } while (0)
; #define PG8_LDA(dst, b, h) do { _Pragma("unroll") for (int m = 0; m < 4; ++m) _Pragma("unroll") for (int k = 0; k < 2; ++k) dst[m][k] = *(const PG8_LAS bf16x8*)(lds + PG8_SA(b, h) + aoff + m * 2048 + k * 1024); } while (0)
; #define PG8_LDB(dst, b, h) do { _Pragma("unroll") for (int n = 0; n < 2; ++n) _Pragma("unroll") for (int k = 0; k < 2; ++k) dst[n][k] = *(const PG8_LAS bf16x8*)(lds + PG8_SB(b, h) + boff + n * 2048 + k * 1024); } while (0)
; #define PG8_MMA(ai, bj, At, Bt) do { __builtin_amdgcn_s_setprio(1); _Pragma("unroll") for (int m = 0; m < 4; ++m) _Pragma("unroll") for (int n = 0; n < 2; ++n) _Pragma("unroll") for (int k = 0; k < 2; ++k) \
;         acc[ai][bj][m][n] = __builtin_amdgcn_mfma_f32_16x16x32_bf16(Bt[n][k], At[m][k], acc[ai][bj][m][n], 0, 0, 0); __builtin_amdgcn_s_setprio(0); } while (0)
; #define PG8_WAIT_V(n) asm volatile("s_waitcnt vmcnt(" #n ")" ::: "memory")
; #define PG8_WAIT_L(n) asm volatile("s_waitcnt lgkmcnt(" #n ")" ::: "memory")
; #define PG8_BAR __builtin_amdgcn_s_barrier()
; #define PG8_SCHED __builtin_amdgcn_sched_barrier(0)
; template <class Epi, class Sched, bool ALIGN_EPI = false, bool SP2 = false>
; __device__ __forceinline__ void gemm_phase(PG8_LAS unsigned char* lds, const Gemm g, const Sched& S, const Epi& E, int wave_s) {
;     ...
;             PG8_WAIT_V(8); PG8_WAIT_L(0); PG8_BAR; PG8_MMA(1, 0, At, B0); PG8_MMA(1, 1, At, B1); PG8_BAR; PG8_SCHED;
;             PG8_LDB(B0, 1, 0); PG8_LDB(B1, 1, 1); PG8_SCHED; PG8_LDA(At, 1, 0); PG8_STAGE(PG8_SA(0, 1), a2 + hstep, voffA);
;             PG8_WAIT_V(8); PG8_WAIT_L(0); PG8_BAR; PG8_MMA(0, 0, At, B0); PG8_MMA(0, 1, At, B1); PG8_BAR; PG8_SCHED;
	v_mfma_f32_16x16x32_bf16 v[60:63], v[176:179], v[180:183], v[60:63]
	v_mfma_f32_16x16x32_bf16 v[60:63], v[172:175], v[184:187], v[60:63]
	v_mfma_f32_16x16x32_bf16 v[56:59], v[164:167], v[184:187], v[56:59]
	v_mfma_f32_16x16x32_bf16 v[56:59], v[168:171], v[180:183], v[56:59]
	v_mfma_f32_16x16x32_bf16 v[40:43], v[168:171], v[188:191], v[40:43]
	v_mfma_f32_16x16x32_bf16 v[40:43], v[164:167], v[192:195], v[40:43]
	v_mfma_f32_16x16x32_bf16 v[44:47], v[172:175], v[192:195], v[44:47]
	v_mfma_f32_16x16x32_bf16 v[44:47], v[176:179], v[188:191], v[44:47]
	v_mfma_f32_16x16x32_bf16 v[28:31], v[176:179], v[196:199], v[28:31]
	v_mfma_f32_16x16x32_bf16 v[28:31], v[172:175], v[200:203], v[28:31]
	v_mfma_f32_16x16x32_bf16 v[24:27], v[164:167], v[200:203], v[24:27]
	v_mfma_f32_16x16x32_bf16 v[24:27], v[168:171], v[196:199], v[24:27]
	v_mfma_f32_16x16x32_bf16 v[8:11], v[168:171], v[204:207], v[8:11]
	v_mfma_f32_16x16x32_bf16 v[8:11], v[164:167], v[208:211], v[8:11]
	v_mfma_f32_16x16x32_bf16 v[12:15], v[172:175], v[208:211], v[12:15]
	v_mfma_f32_16x16x32_bf16 v[12:15], v[176:179], v[204:207], v[12:15]
	v_mfma_f32_16x16x32_bf16 v[52:55], v[160:163], v[180:183], v[52:55]
	v_mfma_f32_16x16x32_bf16 v[52:55], v[156:159], v[184:187], v[52:55]
	v_mfma_f32_16x16x32_bf16 v[48:51], v[144:147], v[184:187], v[48:51]
	v_mfma_f32_16x16x32_bf16 v[48:51], v[152:155], v[180:183], v[48:51]
	v_mfma_f32_16x16x32_bf16 v[32:35], v[152:155], v[188:191], v[32:35]
	v_mfma_f32_16x16x32_bf16 v[32:35], v[144:147], v[192:195], v[32:35]
	v_mfma_f32_16x16x32_bf16 v[36:39], v[156:159], v[192:195], v[36:39]
	v_mfma_f32_16x16x32_bf16 v[36:39], v[160:163], v[188:191], v[36:39]
	v_mfma_f32_16x16x32_bf16 v[20:23], v[160:163], v[196:199], v[20:23]
	v_mfma_f32_16x16x32_bf16 v[20:23], v[156:159], v[200:203], v[20:23]
	v_mfma_f32_16x16x32_bf16 v[16:19], v[144:147], v[200:203], v[16:19]
	v_mfma_f32_16x16x32_bf16 v[16:19], v[152:155], v[196:199], v[16:19]
	v_mfma_f32_16x16x32_bf16 v[0:3], v[152:155], v[204:207], v[0:3]
	v_mfma_f32_16x16x32_bf16 v[0:3], v[144:147], v[208:211], v[0:3]
	v_mfma_f32_16x16x32_bf16 v[4:7], v[156:159], v[208:211], v[4:7]
	v_mfma_f32_16x16x32_bf16 v[4:7], v[160:163], v[204:207], v[4:7]
	s_barrier
	ds_read_b128 v[144:147], v142
	ds_read_b128 v[152:155], v142 offset:1024
	ds_read_b128 v[156:159], v142 offset:2048
	ds_read_b128 v[160:163], v142 offset:3072
	ds_read_b128 v[164:167], v143
	ds_read_b128 v[168:171], v143 offset:1024
	ds_read_b128 v[172:175], v143 offset:2048
	ds_read_b128 v[176:179], v143 offset:3072
	s_add_u32 s48, s48, 0x100000
	s_addc_u32 s49, s49, 0
	s_mov_b32 m0, s58
	v_lshl_add_u64 v[220:221], s[48:49], 0, v[134:135]
	ds_read_b128 v[180:183], v151 offset:32768
	ds_read_b128 v[184:187], v151 offset:33792
	ds_read_b128 v[188:191], v151 offset:34816
	ds_read_b128 v[192:195], v151 offset:35840
	ds_read_b128 v[196:199], v151 offset:36864
	ds_read_b128 v[200:203], v151 offset:37888
	ds_read_b128 v[204:207], v151 offset:38912
	ds_read_b128 v[208:211], v151 offset:39936
	global_load_lds_dwordx4 v[220:221], off
	v_lshl_add_u64 v[220:221], s[48:49], 0, v[130:131]
	s_mov_b32 m0, s59
	s_nop 0
	global_load_lds_dwordx4 v[220:221], off
	s_waitcnt vmcnt(8)
	s_waitcnt lgkmcnt(0)
	s_barrier
	v_mfma_f32_16x16x32_bf16 v[124:127], v[144:147], v[180:183], v[124:127]
	v_mfma_f32_16x16x32_bf16 v[124:127], v[152:155], v[184:187], v[124:127]
	v_mfma_f32_16x16x32_bf16 v[120:123], v[160:163], v[184:187], v[120:123]
	v_mfma_f32_16x16x32_bf16 v[120:123], v[156:159], v[180:183], v[120:123]
	v_mfma_f32_16x16x32_bf16 v[104:107], v[156:159], v[188:191], v[104:107]
	v_mfma_f32_16x16x32_bf16 v[104:107], v[160:163], v[192:195], v[104:107]
	v_mfma_f32_16x16x32_bf16 v[108:111], v[152:155], v[192:195], v[108:111]
	v_mfma_f32_16x16x32_bf16 v[108:111], v[144:147], v[188:191], v[108:111]
	v_mfma_f32_16x16x32_bf16 v[92:95], v[144:147], v[196:199], v[92:95]
	v_mfma_f32_16x16x32_bf16 v[92:95], v[152:155], v[200:203], v[92:95]
	v_mfma_f32_16x16x32_bf16 v[88:91], v[160:163], v[200:203], v[88:91]
	v_mfma_f32_16x16x32_bf16 v[88:91], v[156:159], v[196:199], v[88:91]
	v_mfma_f32_16x16x32_bf16 v[72:75], v[156:159], v[204:207], v[72:75]
	v_mfma_f32_16x16x32_bf16 v[72:75], v[160:163], v[208:211], v[72:75]
	v_mfma_f32_16x16x32_bf16 v[76:79], v[152:155], v[208:211], v[76:79]
	v_mfma_f32_16x16x32_bf16 v[76:79], v[144:147], v[204:207], v[76:79]
	v_mfma_f32_16x16x32_bf16 v[116:119], v[164:167], v[180:183], v[116:119]
	v_mfma_f32_16x16x32_bf16 v[116:119], v[168:171], v[184:187], v[116:119]
	v_mfma_f32_16x16x32_bf16 v[112:115], v[176:179], v[184:187], v[112:115]
	v_mfma_f32_16x16x32_bf16 v[112:115], v[172:175], v[180:183], v[112:115]
	v_mfma_f32_16x16x32_bf16 v[96:99], v[172:175], v[188:191], v[96:99]
	v_mfma_f32_16x16x32_bf16 v[96:99], v[176:179], v[192:195], v[96:99]
	v_mfma_f32_16x16x32_bf16 v[100:103], v[168:171], v[192:195], v[100:103]
	v_mfma_f32_16x16x32_bf16 v[100:103], v[164:167], v[188:191], v[100:103]
	v_mfma_f32_16x16x32_bf16 v[84:87], v[164:167], v[196:199], v[84:87]
	v_mfma_f32_16x16x32_bf16 v[84:87], v[168:171], v[200:203], v[84:87]
	v_mfma_f32_16x16x32_bf16 v[80:83], v[176:179], v[200:203], v[80:83]
	v_mfma_f32_16x16x32_bf16 v[80:83], v[172:175], v[196:199], v[80:83]
	v_mfma_f32_16x16x32_bf16 v[64:67], v[172:175], v[204:207], v[64:67]
	v_mfma_f32_16x16x32_bf16 v[64:67], v[176:179], v[208:211], v[64:67]
	v_mfma_f32_16x16x32_bf16 v[68:71], v[168:171], v[208:211], v[68:71]
	v_mfma_f32_16x16x32_bf16 v[68:71], v[164:167], v[204:207], v[68:71]
	s_barrier
; #define PG8_STAGE(bufoff, gbase, voff) do { _Pragma("unroll") for (int _i = 0; _i < 2; ++_i) \
;         __builtin_amdgcn_global_load_lds((const unsigned*)((const char*)(gbase) + (voff)[_i]), (PG8_LAS unsigned*)(lds + (bufoff) + ldsw + _i * 8192), 16, 0, 0); } while (0)
; #define PG8_LDA(dst, b, h) do { _Pragma("unroll") for (int m = 0; m < 4; ++m) _Pragma("unroll") for (int k = 0; k < 2; ++k) dst[m][k] = *(const PG8_LAS bf16x8*)(lds + PG8_SA(b, h) + aoff + m * 2048 + k * 1024); } while (0)
; #define PG8_MMA(ai, bj, At, Bt) do { __builtin_amdgcn_s_setprio(1); _Pragma("unroll") for (int m = 0; m < 4; ++m) _Pragma("unroll") for (int n = 0; n < 2; ++n) _Pragma("unroll") for (int k = 0; k < 2; ++k) \
;         acc[ai][bj][m][n] = __builtin_amdgcn_mfma_f32_16x16x32_bf16(Bt[n][k], At[m][k], acc[ai][bj][m][n], 0, 0, 0); __builtin_amdgcn_s_setprio(0); } while (0)
; #define PG8_WAIT_V(n) asm volatile("s_waitcnt vmcnt(" #n ")" ::: "memory")
; #define PG8_WAIT_L(n) asm volatile("s_waitcnt lgkmcnt(" #n ")" ::: "memory")
; #define PG8_BAR __builtin_amdgcn_s_barrier()
; #define PG8_SCHED __builtin_amdgcn_sched_barrier(0)
; template <class Epi, class Sched, bool ALIGN_EPI = false, bool SP2 = false>
; __device__ __forceinline__ void gemm_phase(PG8_LAS unsigned char* lds, const Gemm g, const Sched& S, const Epi& E, int wave_s) {
;     ...
;             PG8_LDA(At, 1, 1); PG8_STAGE(PG8_SB(1, 0), b3, voffB); PG8_STAGE(PG8_SB(1, 1), b3 + hstep, voffB); PG8_STAGE(PG8_SA(1, 0), a3, voffA);
;             PG8_WAIT_V(8); PG8_WAIT_L(0); PG8_BAR; PG8_MMA(1, 0, At, B0); PG8_MMA(1, 1, At, B1); PG8_BAR; PG8_SCHED;
;     ...
;         if constexpr (ALIGN_EPI) { if (wr == 0) PG8_BAR; }
	s_mov_b32 m0, s82
	v_lshl_add_u64 v[212:213], v[212:213], 0, s[12:13]
	s_add_u32 s46, s46, 0x100080
	ds_read_b128 v[180:183], v151 offset:49152
	ds_read_b128 v[184:187], v151 offset:50176
	ds_read_b128 v[188:191], v151 offset:51200
	ds_read_b128 v[192:195], v151 offset:52224
	ds_read_b128 v[196:199], v151 offset:53248
	ds_read_b128 v[200:203], v151 offset:54272
	ds_read_b128 v[204:207], v151 offset:55296
	ds_read_b128 v[208:211], v151 offset:56320
	global_load_lds_dwordx4 v[212:213], off
	v_lshl_add_u64 v[212:213], v[214:215], 0, s[12:13]
	s_mov_b32 m0, s83
	s_addc_u32 s47, s47, 0
	global_load_lds_dwordx4 v[212:213], off
	v_lshl_add_u64 v[212:213], s[46:47], 0, v[132:133]
	s_mov_b32 m0, s84
	s_nop 0
	global_load_lds_dwordx4 v[212:213], off
	v_lshl_add_u64 v[212:213], s[46:47], 0, v[128:129]
	s_mov_b32 m0, s85
	s_nop 0
	global_load_lds_dwordx4 v[212:213], off
	v_lshl_add_u64 v[212:213], v[216:217], 0, s[12:13]
	s_mov_b32 m0, s62
	s_nop 0
	global_load_lds_dwordx4 v[212:213], off
	v_lshl_add_u64 v[212:213], v[218:219], 0, s[12:13]
	s_mov_b32 m0, s63
	s_nop 0
	global_load_lds_dwordx4 v[212:213], off
	s_waitcnt vmcnt(8)
	s_waitcnt lgkmcnt(0)
	s_barrier
	v_mfma_f32_16x16x32_bf16 v[60:63], v[144:147], v[180:183], v[60:63]
	v_mfma_f32_16x16x32_bf16 v[60:63], v[152:155], v[184:187], v[60:63]
	v_mfma_f32_16x16x32_bf16 v[56:59], v[160:163], v[184:187], v[56:59]
	v_mfma_f32_16x16x32_bf16 v[56:59], v[156:159], v[180:183], v[56:59]
	v_mfma_f32_16x16x32_bf16 v[40:43], v[156:159], v[188:191], v[40:43]
	v_mfma_f32_16x16x32_bf16 v[40:43], v[160:163], v[192:195], v[40:43]
	v_mfma_f32_16x16x32_bf16 v[44:47], v[152:155], v[192:195], v[44:47]
	v_mfma_f32_16x16x32_bf16 v[44:47], v[144:147], v[188:191], v[44:47]
	v_mfma_f32_16x16x32_bf16 v[28:31], v[144:147], v[196:199], v[28:31]
	v_mfma_f32_16x16x32_bf16 v[28:31], v[152:155], v[200:203], v[28:31]
	v_mfma_f32_16x16x32_bf16 v[24:27], v[160:163], v[200:203], v[24:27]
	v_mfma_f32_16x16x32_bf16 v[24:27], v[156:159], v[196:199], v[24:27]
	v_mfma_f32_16x16x32_bf16 v[8:11], v[156:159], v[204:207], v[8:11]
	v_mfma_f32_16x16x32_bf16 v[8:11], v[160:163], v[208:211], v[8:11]
	v_mfma_f32_16x16x32_bf16 v[12:15], v[152:155], v[208:211], v[12:15]
	v_mfma_f32_16x16x32_bf16 v[12:15], v[144:147], v[204:207], v[12:15]
	v_mfma_f32_16x16x32_bf16 v[52:55], v[164:167], v[180:183], v[52:55]
	v_mfma_f32_16x16x32_bf16 v[52:55], v[168:171], v[184:187], v[52:55]
	v_mfma_f32_16x16x32_bf16 v[48:51], v[176:179], v[184:187], v[48:51]
	v_mfma_f32_16x16x32_bf16 v[48:51], v[172:175], v[180:183], v[48:51]
	v_mfma_f32_16x16x32_bf16 v[32:35], v[172:175], v[188:191], v[32:35]
	v_mfma_f32_16x16x32_bf16 v[32:35], v[176:179], v[192:195], v[32:35]
	v_mfma_f32_16x16x32_bf16 v[36:39], v[168:171], v[192:195], v[36:39]
	v_mfma_f32_16x16x32_bf16 v[36:39], v[164:167], v[188:191], v[36:39]
	v_mfma_f32_16x16x32_bf16 v[20:23], v[164:167], v[196:199], v[20:23]
	v_mfma_f32_16x16x32_bf16 v[20:23], v[168:171], v[200:203], v[20:23]
	v_mfma_f32_16x16x32_bf16 v[16:19], v[176:179], v[200:203], v[16:19]
	v_mfma_f32_16x16x32_bf16 v[16:19], v[172:175], v[196:199], v[16:19]
	v_mfma_f32_16x16x32_bf16 v[0:3], v[172:175], v[204:207], v[0:3]
	v_mfma_f32_16x16x32_bf16 v[0:3], v[176:179], v[208:211], v[0:3]
	v_mfma_f32_16x16x32_bf16 v[4:7], v[168:171], v[208:211], v[4:7]
	v_mfma_f32_16x16x32_bf16 v[4:7], v[164:167], v[204:207], v[4:7]
	s_barrier
	s_add_i32 s88, s88, 2
	s_add_u32 s44, s44, 0x100
	s_addc_u32 s45, s45, 0
	s_add_u32 s86, s86, 0x100
	s_addc_u32 s87, s87, 0
	s_cmp_gt_u32 s88, 61
	s_cbranch_scc0 .LBB0_1343
	s_and_b64 vcc, exec, s[14:15]
	s_cbranch_vccz .LBB0_1346
	s_barrier

; #define PG8_LAS __attribute__((address_space(3)))
; #define PG8_STAGE(bufoff, gbase, voff) do { _Pragma("unroll") for (int _i = 0; _i < 2; ++_i) \
;         __builtin_amdgcn_global_load_lds((const unsigned*)((const char*)(gbase) + (voff)[_i]), (PG8_LAS unsigned*)(lds + (bufoff) + ldsw + _i * 8192), 16, 0, 0); } while (0)
; #define PG8_LDA(dst, b, h) do { _Pragma("unroll") for (int m = 0; m < 4; ++m) _Pragma("unroll") for (int k = 0; k < 2; ++k) dst[m][k] = *(const PG8_LAS bf16x8*)(lds + PG8_SA(b, h) + aoff + m * 2048 + k * 1024); } while (0)
; #define PG8_LDB(dst, b, h) do { _Pragma("unroll") for (int n = 0; n < 2; ++n) _Pragma("unroll") for (int k = 0; k < 2; ++k) dst[n][k] = *(const PG8_LAS bf16x8*)(lds + PG8_SB(b, h) + boff + n * 2048 + k * 1024); } while (0)
; #define PG8_WAIT_V(n) asm volatile("s_waitcnt vmcnt(" #n ")" ::: "memory")
; #define PG8_WAIT_L(n) asm volatile("s_waitcnt lgkmcnt(" #n ")" ::: "memory")
; #define PG8_BAR __builtin_amdgcn_s_barrier()
; #define PG8_SCHED __builtin_amdgcn_sched_barrier(0)
; template <class Epi, class Sched, bool ALIGN_EPI = false, bool SP2 = false>
; __device__ __forceinline__ void gemm_phase(PG8_LAS unsigned char* lds, const Gemm g, const Sched& S, const Epi& E, int wave_s) {
;     ...
;         for (int t = 0; t < nt; t += 2) {
;             const bool last = (t == nt - 2);
;             if constexpr (Epi::NEED_RS) { if (t == 0 && wid < 4) __builtin_amdgcn_global_load_lds((const unsigned*)(E.rstd + cur.pm * BM + wid * 64 + lane), (PG8_LAS unsigned*)(rsl + wid * 64), 4, 0, 0); }
;             const char* a1 = cA + (size_t)(t + 1) * kstep;
;             const char* a2 = last ? nA : cA + (size_t)(t + 2) * kstep; const char* b2 = last ? nB : cB + (size_t)(t + 2) * kstep;
;             const char* a3 = a2 + kstep; const char* b3 = b2 + kstep;
;             if (last && has_next) S.a_ready(nxt);
;             if constexpr (SP2) {
;             PG8_LDB(B0, 0, 0); PG8_LDB(B1, 0, 1); PG8_SCHED; PG8_LDA(At, 0, 0); PG8_STAGE(PG8_SA(1, 1), a1 + hstep, voffA);
;             PG8_WAIT_V(8); PG8_WAIT_L(0); PG8_BAR; PG8_MMA(0, 0, At, B0); PG8_MMA(0, 1, At, B1); PG8_BAR; PG8_SCHED;
;             PG8_LDA(At, 0, 1); PG8_STAGE(PG8_SB(0, 0), b2, voffB); PG8_STAGE(PG8_SB(0, 1), b2 + hstep, voffB); PG8_STAGE(PG8_SA(0, 0), a2, voffA);
.LBB0_1410:
	ds_read_b128 v[128:131], v211
	ds_read_b128 v[132:135], v211 offset:1024
	ds_read_b128 v[136:139], v211 offset:2048
	ds_read_b128 v[140:143], v211 offset:3072
	ds_read_b128 v[144:147], v212
	ds_read_b128 v[148:151], v212 offset:1024
	ds_read_b128 v[152:155], v212 offset:2048
	ds_read_b128 v[156:159], v212 offset:3072
	s_add_u32 s45, s50, 0xffc00080
	s_addc_u32 s52, s51, -1
	s_cmp_eq_u32 s85, s43
	s_cselect_b32 s55, s47, s52
	s_cselect_b32 s54, s46, s45
	s_cselect_b32 s53, s49, s41
	s_cselect_b32 s52, s48, s7
	v_lshl_add_u64 v[204:205], s[50:51], 0, v[192:193]
	s_add_i32 m0, s9, 0xc000
	ds_read_b128 v[160:163], v213
	ds_read_b128 v[164:167], v213 offset:1024
	ds_read_b128 v[168:171], v213 offset:2048
	ds_read_b128 v[172:175], v213 offset:3072
	ds_read_b128 v[176:179], v213 offset:4096
	ds_read_b128 v[180:183], v213 offset:5120
	ds_read_b128 v[196:199], v213 offset:6144
	ds_read_b128 v[200:203], v213 offset:7168
	global_load_lds_dwordx4 v[204:205], off
	v_lshl_add_u64 v[204:205], s[50:51], 0, v[194:195]
	s_add_i32 m0, s9, 0xe000
	s_nop 0
	global_load_lds_dwordx4 v[204:205], off
	s_waitcnt vmcnt(8)
	s_waitcnt lgkmcnt(0)
	s_barrier
	v_mfma_f32_16x16x32_bf16 v[124:127], v[128:131], v[160:163], v[124:127]
	v_mfma_f32_16x16x32_bf16 v[124:127], v[132:135], v[164:167], v[124:127]
	v_mfma_f32_16x16x32_bf16 v[120:123], v[140:143], v[164:167], v[120:123]
	v_mfma_f32_16x16x32_bf16 v[120:123], v[136:139], v[160:163], v[120:123]
	v_mfma_f32_16x16x32_bf16 v[104:107], v[136:139], v[168:171], v[104:107]
	v_mfma_f32_16x16x32_bf16 v[104:107], v[140:143], v[172:175], v[104:107]
	v_mfma_f32_16x16x32_bf16 v[108:111], v[132:135], v[172:175], v[108:111]
	v_mfma_f32_16x16x32_bf16 v[108:111], v[128:131], v[168:171], v[108:111]
	v_mfma_f32_16x16x32_bf16 v[92:95], v[128:131], v[176:179], v[92:95]
	v_mfma_f32_16x16x32_bf16 v[92:95], v[132:135], v[180:183], v[92:95]
	v_mfma_f32_16x16x32_bf16 v[88:91], v[140:143], v[180:183], v[88:91]
	v_mfma_f32_16x16x32_bf16 v[88:91], v[136:139], v[176:179], v[88:91]
	v_mfma_f32_16x16x32_bf16 v[72:75], v[136:139], v[196:199], v[72:75]
	v_mfma_f32_16x16x32_bf16 v[72:75], v[140:143], v[200:203], v[72:75]
	v_mfma_f32_16x16x32_bf16 v[76:79], v[132:135], v[200:203], v[76:79]
	v_mfma_f32_16x16x32_bf16 v[76:79], v[128:131], v[196:199], v[76:79]
	v_mfma_f32_16x16x32_bf16 v[116:119], v[144:147], v[160:163], v[116:119]
	v_mfma_f32_16x16x32_bf16 v[116:119], v[148:151], v[164:167], v[116:119]
	v_mfma_f32_16x16x32_bf16 v[112:115], v[156:159], v[164:167], v[112:115]
	v_mfma_f32_16x16x32_bf16 v[112:115], v[152:155], v[160:163], v[112:115]
	v_mfma_f32_16x16x32_bf16 v[96:99], v[152:155], v[168:171], v[96:99]
	v_mfma_f32_16x16x32_bf16 v[96:99], v[156:159], v[172:175], v[96:99]
	v_mfma_f32_16x16x32_bf16 v[100:103], v[148:151], v[172:175], v[100:103]
	v_mfma_f32_16x16x32_bf16 v[100:103], v[144:147], v[168:171], v[100:103]
	v_mfma_f32_16x16x32_bf16 v[84:87], v[144:147], v[176:179], v[84:87]
	v_mfma_f32_16x16x32_bf16 v[84:87], v[148:151], v[180:183], v[84:87]
	v_mfma_f32_16x16x32_bf16 v[80:83], v[156:159], v[180:183], v[80:83]
	v_mfma_f32_16x16x32_bf16 v[80:83], v[152:155], v[176:179], v[80:83]
	v_mfma_f32_16x16x32_bf16 v[64:67], v[152:155], v[196:199], v[64:67]
	v_mfma_f32_16x16x32_bf16 v[64:67], v[156:159], v[200:203], v[64:67]
	v_mfma_f32_16x16x32_bf16 v[68:71], v[148:151], v[200:203], v[68:71]
	v_mfma_f32_16x16x32_bf16 v[68:71], v[144:147], v[196:199], v[68:71]
	s_barrier
	s_add_i32 s45, s75, s60
	v_lshl_add_u64 v[204:205], s[52:53], 0, v[186:187]
	s_mov_b32 m0, s45
	ds_read_b128 v[160:163], v213 offset:16384
	ds_read_b128 v[164:167], v213 offset:17408
	ds_read_b128 v[168:171], v213 offset:18432
	ds_read_b128 v[172:175], v213 offset:19456
	ds_read_b128 v[176:179], v213 offset:20480
	ds_read_b128 v[180:183], v213 offset:21504
	ds_read_b128 v[196:199], v213 offset:22528
	ds_read_b128 v[200:203], v213 offset:23552
	global_load_lds_dwordx4 v[204:205], off
	s_add_i32 m0, s45, 0x2000
	s_add_u32 s86, s52, 0x400000
	v_lshl_add_u64 v[206:207], s[52:53], 0, v[190:191]
	s_addc_u32 s87, s53, 0
	s_add_i32 s45, s76, s60
	global_load_lds_dwordx4 v[206:207], off
	v_lshl_add_u64 v[208:209], s[86:87], 0, v[186:187]
	s_mov_b32 m0, s45
	v_lshl_add_u64 v[216:217], s[54:55], 0, v[188:189]
	global_load_lds_dwordx4 v[208:209], off
	v_lshl_add_u64 v[208:209], s[86:87], 0, v[190:191]
	s_add_i32 m0, s45, 0x2000
	s_nop 0
	global_load_lds_dwordx4 v[208:209], off
	v_lshl_add_u64 v[208:209], s[54:55], 0, v[184:185]
	s_mov_b32 m0, s9
	s_nop 0
	global_load_lds_dwordx4 v[208:209], off
	s_mov_b32 m0, s61
	s_nop 0
	global_load_lds_dwordx4 v[216:217], off
	s_waitcnt vmcnt(8)
	s_waitcnt lgkmcnt(0)
	s_barrier
; #define PG8_STAGE(bufoff, gbase, voff) do { _Pragma("unroll") for (int _i = 0; _i < 2; ++_i) \
;         __builtin_amdgcn_global_load_lds((const unsigned*)((const char*)(gbase) + (voff)[_i]), (PG8_LAS unsigned*)(lds + (bufoff) + ldsw + _i * 8192), 16, 0, 0); } while (0)
; #define PG8_LDA(dst, b, h) do { _Pragma("unroll") for (int m = 0; m < 4; ++m) _Pragma("unroll") for (int k = 0; k < 2; ++k) dst[m][k] = *(const PG8_LAS bf16x8*)(lds + PG8_SA(b, h) + aoff + m * 2048 + k * 1024); } while (0)
; #define PG8_LDB(dst, b, h) do { _Pragma("unroll") for (int n = 0; n < 2; ++n) _Pragma("unroll") for (int k = 0; k < 2; ++k) dst[n][k] = *(const PG8_LAS bf16x8*)(lds + PG8_SB(b, h) + boff + n * 2048 + k * 1024); } while (0)
; #define PG8_MMA(ai, bj, At, Bt) do { __builtin_amdgcn_s_setprio(1); _Pragma("unroll") for (int m = 0; m < 4; ++m) _Pragma("unroll") for (int n = 0; n < 2; ++n) _Pragma("unroll") for (int k = 0; k < 2; ++k) \
;         acc[ai][bj][m][n] = __builtin_amdgcn_mfma_f32_16x16x32_bf16(Bt[n][k], At[m][k], acc[ai][bj][m][n], 0, 0, 0); __builtin_amdgcn_s_setprio(0); } while (0)
; #define PG8_WAIT_V(n) asm volatile("s_waitcnt vmcnt(" #n ")" ::: "memory")
; #define PG8_WAIT_L(n) asm volatile("s_waitcnt lgkmcnt(" #n ")" ::: "memory")
; #define PG8_BAR __builtin_amdgcn_s_barrier()
; #define PG8_SCHED __builtin_amdgcn_sched_barrier(0)
; template <class Epi, class Sched, bool ALIGN_EPI = false, bool SP2 = false>
; __device__ __forceinline__ void gemm_phase(PG8_LAS unsigned char* lds, const Gemm g, const Sched& S, const Epi& E, int wave_s) {
;     ...
;             PG8_WAIT_V(8); PG8_WAIT_L(0); PG8_BAR; PG8_MMA(1, 0, At, B0); PG8_MMA(1, 1, At, B1); PG8_BAR; PG8_SCHED;
;             PG8_LDB(B0, 1, 0); PG8_LDB(B1, 1, 1); PG8_SCHED; PG8_LDA(At, 1, 0); PG8_STAGE(PG8_SA(0, 1), a2 + hstep, voffA);
;             PG8_WAIT_V(8); PG8_WAIT_L(0); PG8_BAR; PG8_MMA(0, 0, At, B0); PG8_MMA(0, 1, At, B1); PG8_BAR; PG8_SCHED;
	v_mfma_f32_16x16x32_bf16 v[60:63], v[128:131], v[160:163], v[60:63]
	v_mfma_f32_16x16x32_bf16 v[60:63], v[132:135], v[164:167], v[60:63]
	v_mfma_f32_16x16x32_bf16 v[56:59], v[140:143], v[164:167], v[56:59]
	v_mfma_f32_16x16x32_bf16 v[56:59], v[136:139], v[160:163], v[56:59]
	v_mfma_f32_16x16x32_bf16 v[40:43], v[136:139], v[168:171], v[40:43]
	v_mfma_f32_16x16x32_bf16 v[40:43], v[140:143], v[172:175], v[40:43]
	v_mfma_f32_16x16x32_bf16 v[44:47], v[132:135], v[172:175], v[44:47]
	v_mfma_f32_16x16x32_bf16 v[44:47], v[128:131], v[168:171], v[44:47]
	v_mfma_f32_16x16x32_bf16 v[28:31], v[128:131], v[176:179], v[28:31]
	v_mfma_f32_16x16x32_bf16 v[28:31], v[132:135], v[180:183], v[28:31]
	v_mfma_f32_16x16x32_bf16 v[24:27], v[140:143], v[180:183], v[24:27]
	v_mfma_f32_16x16x32_bf16 v[24:27], v[136:139], v[176:179], v[24:27]
	v_mfma_f32_16x16x32_bf16 v[8:11], v[136:139], v[196:199], v[8:11]
	v_mfma_f32_16x16x32_bf16 v[8:11], v[140:143], v[200:203], v[8:11]
	v_mfma_f32_16x16x32_bf16 v[12:15], v[132:135], v[200:203], v[12:15]
	v_mfma_f32_16x16x32_bf16 v[12:15], v[128:131], v[196:199], v[12:15]
	v_mfma_f32_16x16x32_bf16 v[52:55], v[144:147], v[160:163], v[52:55]
	v_mfma_f32_16x16x32_bf16 v[52:55], v[148:151], v[164:167], v[52:55]
	v_mfma_f32_16x16x32_bf16 v[48:51], v[156:159], v[164:167], v[48:51]
	v_mfma_f32_16x16x32_bf16 v[48:51], v[152:155], v[160:163], v[48:51]
	v_mfma_f32_16x16x32_bf16 v[32:35], v[152:155], v[168:171], v[32:35]
	v_mfma_f32_16x16x32_bf16 v[32:35], v[156:159], v[172:175], v[32:35]
	v_mfma_f32_16x16x32_bf16 v[36:39], v[148:151], v[172:175], v[36:39]
	v_mfma_f32_16x16x32_bf16 v[36:39], v[144:147], v[168:171], v[36:39]
	v_mfma_f32_16x16x32_bf16 v[20:23], v[144:147], v[176:179], v[20:23]
	v_mfma_f32_16x16x32_bf16 v[20:23], v[148:151], v[180:183], v[20:23]
	v_mfma_f32_16x16x32_bf16 v[16:19], v[156:159], v[180:183], v[16:19]
	v_mfma_f32_16x16x32_bf16 v[16:19], v[152:155], v[176:179], v[16:19]
	v_mfma_f32_16x16x32_bf16 v[0:3], v[152:155], v[196:199], v[0:3]
	v_mfma_f32_16x16x32_bf16 v[0:3], v[156:159], v[200:203], v[0:3]
	v_mfma_f32_16x16x32_bf16 v[4:7], v[148:151], v[200:203], v[4:7]
	v_mfma_f32_16x16x32_bf16 v[4:7], v[144:147], v[196:199], v[4:7]
	s_barrier
	s_add_i32 s45, 0, 0x18000
	s_add_i32 s86, 0, 0x1c000
	v_add_u32_e32 v140, s45, v210
	v_add_u32_e32 v156, s86, v210
	ds_read_b128 v[128:131], v140
	ds_read_b128 v[132:135], v140 offset:1024
	ds_read_b128 v[136:139], v140 offset:2048
	ds_read_b128 v[140:143], v140 offset:3072
	ds_read_b128 v[144:147], v156
	ds_read_b128 v[148:151], v156 offset:1024
	ds_read_b128 v[152:155], v156 offset:2048
	ds_read_b128 v[156:159], v156 offset:3072
	s_add_u32 s54, s54, 0x400000
	s_addc_u32 s55, s55, 0
	s_mov_b32 m0, s62
	v_lshl_add_u64 v[218:219], s[54:55], 0, v[184:185]
	ds_read_b128 v[160:163], v213 offset:32768
	ds_read_b128 v[164:167], v213 offset:33792
	ds_read_b128 v[168:171], v213 offset:34816
	ds_read_b128 v[172:175], v213 offset:35840
	ds_read_b128 v[176:179], v213 offset:36864
	ds_read_b128 v[180:183], v213 offset:37888
	ds_read_b128 v[196:199], v213 offset:38912
	ds_read_b128 v[200:203], v213 offset:39936
	global_load_lds_dwordx4 v[218:219], off
	v_lshl_add_u64 v[218:219], s[54:55], 0, v[188:189]
	s_mov_b32 m0, s63
	s_nop 0
	global_load_lds_dwordx4 v[218:219], off
	s_waitcnt vmcnt(8)
	s_waitcnt lgkmcnt(0)
	s_barrier
	v_mfma_f32_16x16x32_bf16 v[124:127], v[128:131], v[160:163], v[124:127]
	v_mfma_f32_16x16x32_bf16 v[124:127], v[132:135], v[164:167], v[124:127]
	v_mfma_f32_16x16x32_bf16 v[120:123], v[140:143], v[164:167], v[120:123]
	v_mfma_f32_16x16x32_bf16 v[120:123], v[136:139], v[160:163], v[120:123]
	v_mfma_f32_16x16x32_bf16 v[104:107], v[136:139], v[168:171], v[104:107]
	v_mfma_f32_16x16x32_bf16 v[104:107], v[140:143], v[172:175], v[104:107]
	v_mfma_f32_16x16x32_bf16 v[108:111], v[132:135], v[172:175], v[108:111]
	v_mfma_f32_16x16x32_bf16 v[108:111], v[128:131], v[168:171], v[108:111]
	v_mfma_f32_16x16x32_bf16 v[92:95], v[128:131], v[176:179], v[92:95]
	v_mfma_f32_16x16x32_bf16 v[92:95], v[132:135], v[180:183], v[92:95]
	v_mfma_f32_16x16x32_bf16 v[88:91], v[140:143], v[180:183], v[88:91]
	v_mfma_f32_16x16x32_bf16 v[88:91], v[136:139], v[176:179], v[88:91]
	v_mfma_f32_16x16x32_bf16 v[72:75], v[136:139], v[196:199], v[72:75]
	v_mfma_f32_16x16x32_bf16 v[72:75], v[140:143], v[200:203], v[72:75]
	v_mfma_f32_16x16x32_bf16 v[76:79], v[132:135], v[200:203], v[76:79]
	v_mfma_f32_16x16x32_bf16 v[76:79], v[128:131], v[196:199], v[76:79]
	v_mfma_f32_16x16x32_bf16 v[116:119], v[144:147], v[160:163], v[116:119]
	v_mfma_f32_16x16x32_bf16 v[116:119], v[148:151], v[164:167], v[116:119]
	v_mfma_f32_16x16x32_bf16 v[112:115], v[156:159], v[164:167], v[112:115]
	v_mfma_f32_16x16x32_bf16 v[112:115], v[152:155], v[160:163], v[112:115]
	v_mfma_f32_16x16x32_bf16 v[96:99], v[152:155], v[168:171], v[96:99]
	v_mfma_f32_16x16x32_bf16 v[96:99], v[156:159], v[172:175], v[96:99]
	v_mfma_f32_16x16x32_bf16 v[100:103], v[148:151], v[172:175], v[100:103]
	v_mfma_f32_16x16x32_bf16 v[100:103], v[144:147], v[168:171], v[100:103]
	v_mfma_f32_16x16x32_bf16 v[84:87], v[144:147], v[176:179], v[84:87]
	v_mfma_f32_16x16x32_bf16 v[84:87], v[148:151], v[180:183], v[84:87]
	v_mfma_f32_16x16x32_bf16 v[80:83], v[156:159], v[180:183], v[80:83]
	v_mfma_f32_16x16x32_bf16 v[80:83], v[152:155], v[176:179], v[80:83]
	v_mfma_f32_16x16x32_bf16 v[64:67], v[152:155], v[196:199], v[64:67]
	v_mfma_f32_16x16x32_bf16 v[64:67], v[156:159], v[200:203], v[64:67]
	v_mfma_f32_16x16x32_bf16 v[68:71], v[148:151], v[200:203], v[68:71]
	v_mfma_f32_16x16x32_bf16 v[68:71], v[144:147], v[196:199], v[68:71]
	s_barrier
; #define PG8_STAGE(bufoff, gbase, voff) do { _Pragma("unroll") for (int _i = 0; _i < 2; ++_i) \
;         __builtin_amdgcn_global_load_lds((const unsigned*)((const char*)(gbase) + (voff)[_i]), (PG8_LAS unsigned*)(lds + (bufoff) + ldsw + _i * 8192), 16, 0, 0); } while (0)
; #define PG8_LDA(dst, b, h) do { _Pragma("unroll") for (int m = 0; m < 4; ++m) _Pragma("unroll") for (int k = 0; k < 2; ++k) dst[m][k] = *(const PG8_LAS bf16x8*)(lds + PG8_SA(b, h) + aoff + m * 2048 + k * 1024); } while (0)
; #define PG8_MMA(ai, bj, At, Bt) do { __builtin_amdgcn_s_setprio(1); _Pragma("unroll") for (int m = 0; m < 4; ++m) _Pragma("unroll") for (int n = 0; n < 2; ++n) _Pragma("unroll") for (int k = 0; k < 2; ++k) \
;         acc[ai][bj][m][n] = __builtin_amdgcn_mfma_f32_16x16x32_bf16(Bt[n][k], At[m][k], acc[ai][bj][m][n], 0, 0, 0); __builtin_amdgcn_s_setprio(0); } while (0)
; #define PG8_WAIT_V(n) asm volatile("s_waitcnt vmcnt(" #n ")" ::: "memory")
; #define PG8_WAIT_L(n) asm volatile("s_waitcnt lgkmcnt(" #n ")" ::: "memory")
; #define PG8_BAR __builtin_amdgcn_s_barrier()
; #define PG8_SCHED __builtin_amdgcn_sched_barrier(0)
; template <class Epi, class Sched, bool ALIGN_EPI = false, bool SP2 = false>
; __device__ __forceinline__ void gemm_phase(PG8_LAS unsigned char* lds, const Gemm g, const Sched& S, const Epi& E, int wave_s) {
;     ...
;             PG8_LDA(At, 1, 1); PG8_STAGE(PG8_SB(1, 0), b3, voffB); PG8_STAGE(PG8_SB(1, 1), b3 + hstep, voffB); PG8_STAGE(PG8_SA(1, 0), a3, voffA);
;             PG8_WAIT_V(8); PG8_WAIT_L(0); PG8_BAR; PG8_MMA(1, 0, At, B0); PG8_MMA(1, 1, At, B1); PG8_BAR; PG8_SCHED;
;     ...
;         if constexpr (ALIGN_EPI) { if (wr == 0) PG8_BAR; }
	s_add_i32 s45, s45, s60
	v_lshl_add_u64 v[204:205], v[204:205], 0, s[18:19]
	s_mov_b32 m0, s45
	ds_read_b128 v[160:163], v213 offset:49152
	ds_read_b128 v[164:167], v213 offset:50176
	ds_read_b128 v[168:171], v213 offset:51200
	ds_read_b128 v[172:175], v213 offset:52224
	ds_read_b128 v[176:179], v213 offset:53248
	ds_read_b128 v[180:183], v213 offset:54272
	ds_read_b128 v[196:199], v213 offset:55296
	ds_read_b128 v[200:203], v213 offset:56320
	global_load_lds_dwordx4 v[204:205], off
	s_add_i32 m0, s45, 0x2000
	s_add_u32 s52, s52, 0x400080
	v_lshl_add_u64 v[204:205], v[206:207], 0, s[18:19]
	s_addc_u32 s53, s53, 0
	s_add_i32 s45, s86, s60
	global_load_lds_dwordx4 v[204:205], off
	v_lshl_add_u64 v[204:205], s[52:53], 0, v[186:187]
	s_mov_b32 m0, s45
	s_nop 0
	global_load_lds_dwordx4 v[204:205], off
	v_lshl_add_u64 v[204:205], s[52:53], 0, v[190:191]
	s_add_i32 m0, s45, 0x2000
	s_nop 0
	global_load_lds_dwordx4 v[204:205], off
	v_lshl_add_u64 v[204:205], v[208:209], 0, s[18:19]
	s_mov_b32 m0, s70
	s_nop 0
	global_load_lds_dwordx4 v[204:205], off
	v_lshl_add_u64 v[204:205], v[216:217], 0, s[18:19]
	s_mov_b32 m0, s71
	s_nop 0
	global_load_lds_dwordx4 v[204:205], off
	s_waitcnt vmcnt(8)
	s_waitcnt lgkmcnt(0)
	s_barrier
	v_mfma_f32_16x16x32_bf16 v[60:63], v[128:131], v[160:163], v[60:63]
	v_mfma_f32_16x16x32_bf16 v[60:63], v[132:135], v[164:167], v[60:63]
	v_mfma_f32_16x16x32_bf16 v[56:59], v[140:143], v[164:167], v[56:59]
	v_mfma_f32_16x16x32_bf16 v[56:59], v[136:139], v[160:163], v[56:59]
	v_mfma_f32_16x16x32_bf16 v[40:43], v[136:139], v[168:171], v[40:43]
	v_mfma_f32_16x16x32_bf16 v[40:43], v[140:143], v[172:175], v[40:43]
	v_mfma_f32_16x16x32_bf16 v[44:47], v[132:135], v[172:175], v[44:47]
	v_mfma_f32_16x16x32_bf16 v[44:47], v[128:131], v[168:171], v[44:47]
	v_mfma_f32_16x16x32_bf16 v[28:31], v[128:131], v[176:179], v[28:31]
	v_mfma_f32_16x16x32_bf16 v[28:31], v[132:135], v[180:183], v[28:31]
	v_mfma_f32_16x16x32_bf16 v[24:27], v[140:143], v[180:183], v[24:27]
	v_mfma_f32_16x16x32_bf16 v[24:27], v[136:139], v[176:179], v[24:27]
	v_mfma_f32_16x16x32_bf16 v[8:11], v[136:139], v[196:199], v[8:11]
	v_mfma_f32_16x16x32_bf16 v[8:11], v[140:143], v[200:203], v[8:11]
	v_mfma_f32_16x16x32_bf16 v[12:15], v[132:135], v[200:203], v[12:15]
	v_mfma_f32_16x16x32_bf16 v[12:15], v[128:131], v[196:199], v[12:15]
	v_mfma_f32_16x16x32_bf16 v[52:55], v[144:147], v[160:163], v[52:55]
	v_mfma_f32_16x16x32_bf16 v[52:55], v[148:151], v[164:167], v[52:55]
	v_mfma_f32_16x16x32_bf16 v[48:51], v[156:159], v[164:167], v[48:51]
	v_mfma_f32_16x16x32_bf16 v[48:51], v[152:155], v[160:163], v[48:51]
	v_mfma_f32_16x16x32_bf16 v[32:35], v[152:155], v[168:171], v[32:35]
	v_mfma_f32_16x16x32_bf16 v[32:35], v[156:159], v[172:175], v[32:35]
	v_mfma_f32_16x16x32_bf16 v[36:39], v[148:151], v[172:175], v[36:39]
	v_mfma_f32_16x16x32_bf16 v[36:39], v[144:147], v[168:171], v[36:39]
	v_mfma_f32_16x16x32_bf16 v[20:23], v[144:147], v[176:179], v[20:23]
	v_mfma_f32_16x16x32_bf16 v[20:23], v[148:151], v[180:183], v[20:23]
	v_mfma_f32_16x16x32_bf16 v[16:19], v[156:159], v[180:183], v[16:19]
	v_mfma_f32_16x16x32_bf16 v[16:19], v[152:155], v[176:179], v[16:19]
	v_mfma_f32_16x16x32_bf16 v[0:3], v[152:155], v[196:199], v[0:3]
	v_mfma_f32_16x16x32_bf16 v[0:3], v[156:159], v[200:203], v[0:3]
	v_mfma_f32_16x16x32_bf16 v[4:7], v[148:151], v[200:203], v[4:7]
	v_mfma_f32_16x16x32_bf16 v[4:7], v[144:147], v[196:199], v[4:7]
	s_barrier
	s_add_i32 s45, s43, 2
	s_add_u32 s50, s50, 0x100
	s_addc_u32 s51, s51, 0
	s_add_u32 s7, s7, 0x100
	s_addc_u32 s41, s41, 0
	s_cmp_ge_i32 s43, s85
	s_mov_b32 s43, s45
	s_cbranch_scc0 .LBB0_1410
	s_and_b64 vcc, exec, s[20:21]
	s_cbranch_vccz .LBB0_1413
	s_barrier
